# GEMM K-loops: duplicate back-to-back s_waitcnt lgkmcnt(0) removed (24 sites), on top of the static younger-half priority
# speedup vs baseline: 1.0162x; 1.0020x over previous
; #define PG8_STAGE(bufoff, gbase, voff) do { _Pragma("unroll") for (int _i = 0; _i < 2; ++_i) \
;         __builtin_amdgcn_global_load_lds((const unsigned*)((const char*)(gbase) + (voff)[_i]), (LAS unsigned*)(lds + (bufoff) + ldsw + _i * 8192), 16, 0, 0); } while (0)
; #define PG8_LDA(dst, b, h) do { _Pragma("unroll") for (int m = 0; m < 4; ++m) _Pragma("unroll") for (int k = 0; k < 2; ++k) dst[m][k] = *(const LAS bf16x8*)(lds + PG8_SA(b, h) + aoff + m * 2048 + k * 1024); } while (0)
; #define PG8_LDB(dst, b, h) do { _Pragma("unroll") for (int n = 0; n < 2; ++n) _Pragma("unroll") for (int k = 0; k < 2; ++k) dst[n][k] = *(const LAS bf16x8*)(lds + PG8_SB(b, h) + boff + n * 2048 + k * 1024); } while (0)
; #define PG8_MMA(ai, bj, At, Bt) do { __builtin_amdgcn_s_setprio(1); _Pragma("unroll") for (int m = 0; m < 4; ++m) _Pragma("unroll") for (int n = 0; n < 2; ++n) _Pragma("unroll") for (int k = 0; k < 2; ++k) \
;         acc[ai][bj][m][n] = __builtin_amdgcn_mfma_f32_16x16x32_bf16(Bt[n][k], At[m][k], acc[ai][bj][m][n], 0, 0, 0); __builtin_amdgcn_s_setprio(0); } while (0)
; #define PG8_WAIT_L(n) asm volatile("s_waitcnt lgkmcnt(" #n ")" ::: "memory")
; #define PG8_BAR __builtin_amdgcn_s_barrier()
; #define PG8_SCHED __builtin_amdgcn_sched_barrier(0)
; template <class Epi>
; __device__ __forceinline__ void gemm_phase(LAS unsigned char* lds, const Gemm g, const StaticOrder& S, const Epi& E) {
;     ...
;             const bool last = (t == nt - 2);
;             const char* a1 = cA + (size_t)(t + 1) * kstep;
;             const char* a2 = last ? nA : cA + (size_t)(t + 2) * kstep; const char* b2 = last ? nB : cB + (size_t)(t + 2) * kstep;
;             const char* a3 = a2 + kstep; const char* b3 = b2 + kstep;
;             PG8_LDB(B0, 0, 0); PG8_SCHED; PG8_LDA(At, 0, 0); PG8_STAGE(PG8_SA(1, 1), a1 + hstep, voffA);
;             PG8_WAIT_L(8); PG8_BAR; PG8_WAIT_L(0); PG8_MMA(0, 0, At, B0); PG8_BAR; PG8_SCHED;
;             PG8_LDB(B1, 0, 1); PG8_STAGE(PG8_SB(0, 0), b2, voffB);
;             PG8_BAR; PG8_WAIT_L(0); PG8_MMA(0, 1, At, B1); PG8_BAR;
;             PG8_LDA(At, 0, 1); PG8_STAGE(PG8_SA(0, 0), a2, voffA);
;             PG8_BAR; PG8_WAIT_L(0); PG8_MMA(1, 0, At, B0); PG8_BAR; PG8_SCHED;
.LBB0_568:
	s_add_i32 s74, s52, 2
	s_add_u32 s30, s50, 0xfffc0080
	s_addc_u32 s31, s51, -1
	s_add_i32 s75, 0, 0x10000
	v_add_u32_e32 v158, s75, v163
	ds_read_b128 v[136:139], v158
	ds_read_b128 v[150:153], v158 offset:1024
	ds_read_b128 v[154:157], v158 offset:2048
	ds_read_b128 v[158:161], v158 offset:3072
	s_cmp_eq_u32 s63, s52
	s_cselect_b32 s52, s61, s72
	s_cselect_b32 s71, s33, s31
	s_cselect_b32 s70, s38, s30
	s_cselect_b32 s53, s39, s73
	v_lshl_add_u64 v[182:183], s[50:51], 0, v[148:149]
	s_add_i32 m0, s18, 0xc000
	ds_read_b128 v[166:169], v165
	ds_read_b128 v[170:173], v165 offset:1024
	ds_read_b128 v[174:177], v165 offset:2048
	ds_read_b128 v[178:181], v165 offset:3072
	ds_read_b128 v[186:189], v165 offset:4096
	ds_read_b128 v[190:193], v165 offset:5120
	ds_read_b128 v[194:197], v165 offset:6144
	ds_read_b128 v[198:201], v165 offset:7168
	global_load_lds_dwordx4 v[182:183], off
	v_lshl_add_u64 v[182:183], s[50:51], 0, v[146:147]
	s_add_i32 m0, s18, 0xe000
	s_nop 0
	global_load_lds_dwordx4 v[182:183], off
	s_waitcnt lgkmcnt(8)
	s_barrier
	s_waitcnt lgkmcnt(0)
	v_mfma_f32_16x16x32_bf16 v[132:135], v[136:139], v[166:169], v[132:135]
	v_mfma_f32_16x16x32_bf16 v[128:131], v[154:157], v[166:169], v[128:131]
	v_mfma_f32_16x16x32_bf16 v[116:119], v[136:139], v[174:177], v[116:119]
	v_mfma_f32_16x16x32_bf16 v[112:115], v[154:157], v[174:177], v[112:115]
	v_mfma_f32_16x16x32_bf16 v[100:103], v[136:139], v[186:189], v[100:103]
	v_mfma_f32_16x16x32_bf16 v[96:99], v[154:157], v[186:189], v[96:99]
	v_mfma_f32_16x16x32_bf16 v[84:87], v[136:139], v[194:197], v[84:87]
	v_mfma_f32_16x16x32_bf16 v[80:83], v[154:157], v[194:197], v[80:83]
	v_mfma_f32_16x16x32_bf16 v[132:135], v[150:153], v[170:173], v[132:135]
	v_mfma_f32_16x16x32_bf16 v[128:131], v[158:161], v[170:173], v[128:131]
	v_mfma_f32_16x16x32_bf16 v[116:119], v[150:153], v[178:181], v[116:119]
	v_mfma_f32_16x16x32_bf16 v[112:115], v[158:161], v[178:181], v[112:115]
	v_mfma_f32_16x16x32_bf16 v[100:103], v[150:153], v[190:193], v[100:103]
	v_mfma_f32_16x16x32_bf16 v[96:99], v[158:161], v[190:193], v[96:99]
	v_mfma_f32_16x16x32_bf16 v[84:87], v[150:153], v[198:201], v[84:87]
	v_mfma_f32_16x16x32_bf16 v[80:83], v[158:161], v[198:201], v[80:83]
	s_barrier
	s_add_i32 s76, 0, 0x14000
	v_add_u32_e32 v182, s76, v163
	s_add_i32 s30, s75, s6
	ds_read_b128 v[232:235], v182
	ds_read_b128 v[236:239], v182 offset:1024
	ds_read_b128 v[240:243], v182 offset:2048
	ds_read_b128 v[244:247], v182 offset:3072
	v_lshl_add_u64 v[182:183], s[52:53], 0, v[0:1]
	s_mov_b32 m0, s30
	v_lshl_add_u64 v[248:249], s[52:53], 0, v[2:3]
	global_load_lds_dwordx4 v[182:183], off
	s_add_i32 m0, s30, 0x2000
	s_nop 0
	global_load_lds_dwordx4 v[248:249], off
	s_barrier
	s_waitcnt lgkmcnt(0)
	v_mfma_f32_16x16x32_bf16 v[124:127], v[232:235], v[166:169], v[124:127]
	v_mfma_f32_16x16x32_bf16 v[120:123], v[240:243], v[166:169], v[120:123]
	v_mfma_f32_16x16x32_bf16 v[108:111], v[232:235], v[174:177], v[108:111]
	v_mfma_f32_16x16x32_bf16 v[104:107], v[240:243], v[174:177], v[104:107]
	v_mfma_f32_16x16x32_bf16 v[92:95], v[232:235], v[186:189], v[92:95]
	v_mfma_f32_16x16x32_bf16 v[88:91], v[240:243], v[186:189], v[88:91]
	v_mfma_f32_16x16x32_bf16 v[76:79], v[232:235], v[194:197], v[76:79]
	v_mfma_f32_16x16x32_bf16 v[72:75], v[240:243], v[194:197], v[72:75]
	v_mfma_f32_16x16x32_bf16 v[124:127], v[236:239], v[170:173], v[124:127]
	v_mfma_f32_16x16x32_bf16 v[120:123], v[244:247], v[170:173], v[120:123]
	v_mfma_f32_16x16x32_bf16 v[108:111], v[236:239], v[178:181], v[108:111]
	v_mfma_f32_16x16x32_bf16 v[104:107], v[244:247], v[178:181], v[104:107]
	v_mfma_f32_16x16x32_bf16 v[92:95], v[236:239], v[190:193], v[92:95]
	v_mfma_f32_16x16x32_bf16 v[88:91], v[244:247], v[190:193], v[88:91]
	v_mfma_f32_16x16x32_bf16 v[76:79], v[236:239], v[198:201], v[76:79]
	v_mfma_f32_16x16x32_bf16 v[72:75], v[244:247], v[198:201], v[72:75]
	s_mov_b32 m0, s18
	v_lshl_add_u64 v[250:251], s[70:71], 0, v[142:143]
	s_barrier
	ds_read_b128 v[166:169], v165 offset:16384
	ds_read_b128 v[170:173], v165 offset:17408
	ds_read_b128 v[174:177], v165 offset:18432
	ds_read_b128 v[178:181], v165 offset:19456
	ds_read_b128 v[186:189], v165 offset:20480
	ds_read_b128 v[190:193], v165 offset:21504
	ds_read_b128 v[194:197], v165 offset:22528
	ds_read_b128 v[198:201], v165 offset:23552
	global_load_lds_dwordx4 v[250:251], off
	v_lshl_add_u64 v[218:219], s[70:71], 0, v[140:141]
	s_mov_b32 m0, s19
	s_nop 0
	global_load_lds_dwordx4 v[218:219], off
	s_barrier
	s_waitcnt lgkmcnt(0)
	v_mfma_f32_16x16x32_bf16 v[68:71], v[136:139], v[166:169], v[68:71]
	v_mfma_f32_16x16x32_bf16 v[64:67], v[154:157], v[166:169], v[64:67]
	v_mfma_f32_16x16x32_bf16 v[52:55], v[136:139], v[174:177], v[52:55]
	v_mfma_f32_16x16x32_bf16 v[48:51], v[154:157], v[174:177], v[48:51]
	v_mfma_f32_16x16x32_bf16 v[36:39], v[136:139], v[186:189], v[36:39]
	v_mfma_f32_16x16x32_bf16 v[32:35], v[154:157], v[186:189], v[32:35]
	v_mfma_f32_16x16x32_bf16 v[20:23], v[136:139], v[194:197], v[20:23]
	v_mfma_f32_16x16x32_bf16 v[16:19], v[154:157], v[194:197], v[16:19]
	v_mfma_f32_16x16x32_bf16 v[68:71], v[150:153], v[170:173], v[68:71]
	v_mfma_f32_16x16x32_bf16 v[64:67], v[158:161], v[170:173], v[64:67]
	v_mfma_f32_16x16x32_bf16 v[52:55], v[150:153], v[178:181], v[52:55]
	v_mfma_f32_16x16x32_bf16 v[48:51], v[158:161], v[178:181], v[48:51]
	v_mfma_f32_16x16x32_bf16 v[36:39], v[150:153], v[190:193], v[36:39]
	v_mfma_f32_16x16x32_bf16 v[32:35], v[158:161], v[190:193], v[32:35]
	v_mfma_f32_16x16x32_bf16 v[20:23], v[150:153], v[198:201], v[20:23]
	v_mfma_f32_16x16x32_bf16 v[16:19], v[158:161], v[198:201], v[16:19]
	s_barrier
; #define PG8_STAGE(bufoff, gbase, voff) do { _Pragma("unroll") for (int _i = 0; _i < 2; ++_i) \
;         __builtin_amdgcn_global_load_lds((const unsigned*)((const char*)(gbase) + (voff)[_i]), (LAS unsigned*)(lds + (bufoff) + ldsw + _i * 8192), 16, 0, 0); } while (0)
; #define PG8_LDA(dst, b, h) do { _Pragma("unroll") for (int m = 0; m < 4; ++m) _Pragma("unroll") for (int k = 0; k < 2; ++k) dst[m][k] = *(const LAS bf16x8*)(lds + PG8_SA(b, h) + aoff + m * 2048 + k * 1024); } while (0)
; #define PG8_LDB(dst, b, h) do { _Pragma("unroll") for (int n = 0; n < 2; ++n) _Pragma("unroll") for (int k = 0; k < 2; ++k) dst[n][k] = *(const LAS bf16x8*)(lds + PG8_SB(b, h) + boff + n * 2048 + k * 1024); } while (0)
; #define PG8_MMA(ai, bj, At, Bt) do { __builtin_amdgcn_s_setprio(1); _Pragma("unroll") for (int m = 0; m < 4; ++m) _Pragma("unroll") for (int n = 0; n < 2; ++n) _Pragma("unroll") for (int k = 0; k < 2; ++k) \
;         acc[ai][bj][m][n] = __builtin_amdgcn_mfma_f32_16x16x32_bf16(Bt[n][k], At[m][k], acc[ai][bj][m][n], 0, 0, 0); __builtin_amdgcn_s_setprio(0); } while (0)
; #define PG8_WAIT_V(n) asm volatile("s_waitcnt vmcnt(" #n ")" ::: "memory")
; #define PG8_WAIT_L(n) asm volatile("s_waitcnt lgkmcnt(" #n ")" ::: "memory")
; #define PG8_BAR __builtin_amdgcn_s_barrier()
; #define PG8_SCHED __builtin_amdgcn_sched_barrier(0)
; template <class Epi>
; __device__ __forceinline__ void gemm_phase(LAS unsigned char* lds, const Gemm g, const StaticOrder& S, const Epi& E) {
;     ...
;             PG8_STAGE(PG8_SB(0, 1), b2 + hstep, voffB);
;             PG8_WAIT_V(6); PG8_BAR; PG8_MMA(1, 1, At, B1); PG8_BAR;
;             PG8_LDB(B0, 1, 0); PG8_SCHED; PG8_LDA(At, 1, 0); PG8_STAGE(PG8_SA(0, 1), a2 + hstep, voffA);
;             PG8_WAIT_L(8); PG8_BAR; PG8_WAIT_L(0); PG8_MMA(0, 0, At, B0); PG8_BAR; PG8_SCHED;
;             PG8_LDB(B1, 1, 1); PG8_STAGE(PG8_SB(1, 0), b3, voffB);
;             PG8_BAR; PG8_WAIT_L(0); PG8_MMA(0, 1, At, B1); PG8_BAR;
	s_add_u32 s30, s52, 0x40000
	s_addc_u32 s31, s53, 0
	s_add_i32 s75, s76, s6
	v_lshl_add_u64 v[136:137], s[30:31], 0, v[0:1]
	s_mov_b32 m0, s75
	s_nop 0
	global_load_lds_dwordx4 v[136:137], off
	v_lshl_add_u64 v[136:137], s[30:31], 0, v[2:3]
	s_add_i32 m0, s75, 0x2000
	s_nop 0
	global_load_lds_dwordx4 v[136:137], off
	s_waitcnt vmcnt(6)
	s_barrier
	v_mfma_f32_16x16x32_bf16 v[60:63], v[232:235], v[166:169], v[60:63]
	v_mfma_f32_16x16x32_bf16 v[56:59], v[240:243], v[166:169], v[56:59]
	v_mfma_f32_16x16x32_bf16 v[44:47], v[232:235], v[174:177], v[44:47]
	v_mfma_f32_16x16x32_bf16 v[40:43], v[240:243], v[174:177], v[40:43]
	v_mfma_f32_16x16x32_bf16 v[28:31], v[232:235], v[186:189], v[28:31]
	v_mfma_f32_16x16x32_bf16 v[24:27], v[240:243], v[186:189], v[24:27]
	v_mfma_f32_16x16x32_bf16 v[12:15], v[232:235], v[194:197], v[12:15]
	v_mfma_f32_16x16x32_bf16 v[8:11], v[240:243], v[194:197], v[8:11]
	v_mfma_f32_16x16x32_bf16 v[60:63], v[236:239], v[170:173], v[60:63]
	v_mfma_f32_16x16x32_bf16 v[56:59], v[244:247], v[170:173], v[56:59]
	v_mfma_f32_16x16x32_bf16 v[44:47], v[236:239], v[178:181], v[44:47]
	v_mfma_f32_16x16x32_bf16 v[40:43], v[244:247], v[178:181], v[40:43]
	v_mfma_f32_16x16x32_bf16 v[28:31], v[236:239], v[190:193], v[28:31]
	v_mfma_f32_16x16x32_bf16 v[24:27], v[244:247], v[190:193], v[24:27]
	v_mfma_f32_16x16x32_bf16 v[12:15], v[236:239], v[198:201], v[12:15]
	v_mfma_f32_16x16x32_bf16 v[8:11], v[244:247], v[198:201], v[8:11]
	s_add_i32 s75, 0, 0x18000
	v_add_u32_e32 v158, s75, v163
	s_barrier
	ds_read_b128 v[136:139], v158
	ds_read_b128 v[150:153], v158 offset:1024
	ds_read_b128 v[154:157], v158 offset:2048
	ds_read_b128 v[158:161], v158 offset:3072
	s_add_u32 s30, s70, 0x40000
	s_addc_u32 s31, s71, 0
	s_mov_b32 m0, s20
	v_lshl_add_u64 v[232:233], s[30:31], 0, v[142:143]
	ds_read_b128 v[166:169], v165 offset:32768
	ds_read_b128 v[170:173], v165 offset:33792
	ds_read_b128 v[174:177], v165 offset:34816
	ds_read_b128 v[178:181], v165 offset:35840
	ds_read_b128 v[186:189], v165 offset:36864
	ds_read_b128 v[190:193], v165 offset:37888
	ds_read_b128 v[194:197], v165 offset:38912
	ds_read_b128 v[198:201], v165 offset:39936
	global_load_lds_dwordx4 v[232:233], off
	v_lshl_add_u64 v[232:233], s[30:31], 0, v[140:141]
	s_mov_b32 m0, s21
	s_nop 0
	global_load_lds_dwordx4 v[232:233], off
	s_waitcnt lgkmcnt(8)
	s_barrier
	s_waitcnt lgkmcnt(0)
	v_mfma_f32_16x16x32_bf16 v[132:135], v[136:139], v[166:169], v[132:135]
	v_mfma_f32_16x16x32_bf16 v[128:131], v[154:157], v[166:169], v[128:131]
	v_mfma_f32_16x16x32_bf16 v[116:119], v[136:139], v[174:177], v[116:119]
	v_mfma_f32_16x16x32_bf16 v[112:115], v[154:157], v[174:177], v[112:115]
	v_mfma_f32_16x16x32_bf16 v[100:103], v[136:139], v[186:189], v[100:103]
	v_mfma_f32_16x16x32_bf16 v[96:99], v[154:157], v[186:189], v[96:99]
	v_mfma_f32_16x16x32_bf16 v[84:87], v[136:139], v[194:197], v[84:87]
	v_mfma_f32_16x16x32_bf16 v[80:83], v[154:157], v[194:197], v[80:83]
	v_mfma_f32_16x16x32_bf16 v[132:135], v[150:153], v[170:173], v[132:135]
	v_mfma_f32_16x16x32_bf16 v[128:131], v[158:161], v[170:173], v[128:131]
	v_mfma_f32_16x16x32_bf16 v[116:119], v[150:153], v[178:181], v[116:119]
	v_mfma_f32_16x16x32_bf16 v[112:115], v[158:161], v[178:181], v[112:115]
	v_mfma_f32_16x16x32_bf16 v[100:103], v[150:153], v[190:193], v[100:103]
	v_mfma_f32_16x16x32_bf16 v[96:99], v[158:161], v[190:193], v[96:99]
	v_mfma_f32_16x16x32_bf16 v[84:87], v[150:153], v[198:201], v[84:87]
	v_mfma_f32_16x16x32_bf16 v[80:83], v[158:161], v[198:201], v[80:83]
	s_barrier
	s_add_i32 s70, 0, 0x1c000
	s_add_i32 s30, s75, s6
	v_add_u32_e32 v185, s70, v163
	v_lshl_add_u64 v[182:183], v[182:183], 0, s[12:13]
	s_mov_b32 m0, s30
	ds_read_b128 v[232:235], v185
	ds_read_b128 v[236:239], v185 offset:1024
	ds_read_b128 v[240:243], v185 offset:2048
	ds_read_b128 v[244:247], v185 offset:3072
	global_load_lds_dwordx4 v[182:183], off
	v_lshl_add_u64 v[182:183], v[248:249], 0, s[12:13]
	s_add_i32 m0, s30, 0x2000
	s_nop 0
	global_load_lds_dwordx4 v[182:183], off
	s_barrier
; #define PG8_STAGE(bufoff, gbase, voff) do { _Pragma("unroll") for (int _i = 0; _i < 2; ++_i) \
;         __builtin_amdgcn_global_load_lds((const unsigned*)((const char*)(gbase) + (voff)[_i]), (LAS unsigned*)(lds + (bufoff) + ldsw + _i * 8192), 16, 0, 0); } while (0)
; #define PG8_LDA(dst, b, h) do { _Pragma("unroll") for (int m = 0; m < 4; ++m) _Pragma("unroll") for (int k = 0; k < 2; ++k) dst[m][k] = *(const LAS bf16x8*)(lds + PG8_SA(b, h) + aoff + m * 2048 + k * 1024); } while (0)
; #define PG8_MMA(ai, bj, At, Bt) do { __builtin_amdgcn_s_setprio(1); _Pragma("unroll") for (int m = 0; m < 4; ++m) _Pragma("unroll") for (int n = 0; n < 2; ++n) _Pragma("unroll") for (int k = 0; k < 2; ++k) \
;         acc[ai][bj][m][n] = __builtin_amdgcn_mfma_f32_16x16x32_bf16(Bt[n][k], At[m][k], acc[ai][bj][m][n], 0, 0, 0); __builtin_amdgcn_s_setprio(0); } while (0)
; #define PG8_WAIT_V(n) asm volatile("s_waitcnt vmcnt(" #n ")" ::: "memory")
; #define PG8_WAIT_L(n) asm volatile("s_waitcnt lgkmcnt(" #n ")" ::: "memory")
; #define PG8_BAR __builtin_amdgcn_s_barrier()
; #define PG8_SCHED __builtin_amdgcn_sched_barrier(0)
; template <class Epi>
; __device__ __forceinline__ void gemm_phase(LAS unsigned char* lds, const Gemm g, const StaticOrder& S, const Epi& E) {
;     ...
;             PG8_BAR; PG8_WAIT_L(0); PG8_MMA(0, 1, At, B1); PG8_BAR;
;             PG8_LDA(At, 1, 1); PG8_STAGE(PG8_SA(1, 0), a3, voffA);
;             PG8_BAR; PG8_WAIT_L(0); PG8_MMA(1, 0, At, B0); PG8_BAR; PG8_SCHED;
;             PG8_STAGE(PG8_SB(1, 1), b3 + hstep, voffB);
;             PG8_WAIT_V(6); PG8_BAR; PG8_MMA(1, 1, At, B1); PG8_BAR;
	s_waitcnt lgkmcnt(0)
	v_mfma_f32_16x16x32_bf16 v[124:127], v[232:235], v[166:169], v[124:127]
	v_mfma_f32_16x16x32_bf16 v[120:123], v[240:243], v[166:169], v[120:123]
	v_mfma_f32_16x16x32_bf16 v[108:111], v[232:235], v[174:177], v[108:111]
	v_mfma_f32_16x16x32_bf16 v[104:107], v[240:243], v[174:177], v[104:107]
	v_mfma_f32_16x16x32_bf16 v[92:95], v[232:235], v[186:189], v[92:95]
	v_mfma_f32_16x16x32_bf16 v[88:91], v[240:243], v[186:189], v[88:91]
	v_mfma_f32_16x16x32_bf16 v[76:79], v[232:235], v[194:197], v[76:79]
	v_mfma_f32_16x16x32_bf16 v[72:75], v[240:243], v[194:197], v[72:75]
	v_mfma_f32_16x16x32_bf16 v[124:127], v[236:239], v[170:173], v[124:127]
	v_mfma_f32_16x16x32_bf16 v[120:123], v[244:247], v[170:173], v[120:123]
	v_mfma_f32_16x16x32_bf16 v[108:111], v[236:239], v[178:181], v[108:111]
	v_mfma_f32_16x16x32_bf16 v[104:107], v[244:247], v[178:181], v[104:107]
	v_mfma_f32_16x16x32_bf16 v[92:95], v[236:239], v[190:193], v[92:95]
	v_mfma_f32_16x16x32_bf16 v[88:91], v[244:247], v[190:193], v[88:91]
	v_mfma_f32_16x16x32_bf16 v[76:79], v[236:239], v[198:201], v[76:79]
	v_mfma_f32_16x16x32_bf16 v[72:75], v[244:247], v[198:201], v[72:75]
	s_mov_b32 m0, s22
	v_lshl_add_u64 v[182:183], v[250:251], 0, s[12:13]
	s_barrier
	ds_read_b128 v[166:169], v165 offset:49152
	ds_read_b128 v[170:173], v165 offset:50176
	ds_read_b128 v[174:177], v165 offset:51200
	ds_read_b128 v[178:181], v165 offset:52224
	ds_read_b128 v[186:189], v165 offset:53248
	ds_read_b128 v[190:193], v165 offset:54272
	ds_read_b128 v[194:197], v165 offset:55296
	ds_read_b128 v[198:201], v165 offset:56320
	global_load_lds_dwordx4 v[182:183], off
	v_lshl_add_u64 v[182:183], v[218:219], 0, s[12:13]
	s_mov_b32 m0, s23
	s_nop 0
	global_load_lds_dwordx4 v[182:183], off
	s_barrier
	s_waitcnt lgkmcnt(0)
	v_mfma_f32_16x16x32_bf16 v[68:71], v[136:139], v[166:169], v[68:71]
	v_mfma_f32_16x16x32_bf16 v[64:67], v[154:157], v[166:169], v[64:67]
	v_mfma_f32_16x16x32_bf16 v[52:55], v[136:139], v[174:177], v[52:55]
	v_mfma_f32_16x16x32_bf16 v[48:51], v[154:157], v[174:177], v[48:51]
	v_mfma_f32_16x16x32_bf16 v[36:39], v[136:139], v[186:189], v[36:39]
	v_mfma_f32_16x16x32_bf16 v[32:35], v[154:157], v[186:189], v[32:35]
	v_mfma_f32_16x16x32_bf16 v[20:23], v[136:139], v[194:197], v[20:23]
	v_mfma_f32_16x16x32_bf16 v[16:19], v[154:157], v[194:197], v[16:19]
	v_mfma_f32_16x16x32_bf16 v[68:71], v[150:153], v[170:173], v[68:71]
	v_mfma_f32_16x16x32_bf16 v[64:67], v[158:161], v[170:173], v[64:67]
	v_mfma_f32_16x16x32_bf16 v[52:55], v[150:153], v[178:181], v[52:55]
	v_mfma_f32_16x16x32_bf16 v[48:51], v[158:161], v[178:181], v[48:51]
	v_mfma_f32_16x16x32_bf16 v[36:39], v[150:153], v[190:193], v[36:39]
	v_mfma_f32_16x16x32_bf16 v[32:35], v[158:161], v[190:193], v[32:35]
	v_mfma_f32_16x16x32_bf16 v[20:23], v[150:153], v[198:201], v[20:23]
	v_mfma_f32_16x16x32_bf16 v[16:19], v[158:161], v[198:201], v[16:19]
	s_barrier
	s_add_u32 s30, s52, 0x40080
	s_addc_u32 s31, s53, 0
	s_add_i32 s52, s70, s6
	v_lshl_add_u64 v[136:137], s[30:31], 0, v[0:1]
	s_mov_b32 m0, s52
	s_nop 0
	global_load_lds_dwordx4 v[136:137], off
	v_lshl_add_u64 v[136:137], s[30:31], 0, v[2:3]
	s_add_i32 m0, s52, 0x2000
	s_nop 0
	global_load_lds_dwordx4 v[136:137], off
	s_waitcnt vmcnt(6)
	s_barrier
	v_mfma_f32_16x16x32_bf16 v[60:63], v[232:235], v[166:169], v[60:63]
	v_mfma_f32_16x16x32_bf16 v[56:59], v[240:243], v[166:169], v[56:59]
	v_mfma_f32_16x16x32_bf16 v[44:47], v[232:235], v[174:177], v[44:47]
	v_mfma_f32_16x16x32_bf16 v[40:43], v[240:243], v[174:177], v[40:43]
	v_mfma_f32_16x16x32_bf16 v[28:31], v[232:235], v[186:189], v[28:31]
	v_mfma_f32_16x16x32_bf16 v[24:27], v[240:243], v[186:189], v[24:27]
	v_mfma_f32_16x16x32_bf16 v[12:15], v[232:235], v[194:197], v[12:15]
	v_mfma_f32_16x16x32_bf16 v[8:11], v[240:243], v[194:197], v[8:11]
	v_mfma_f32_16x16x32_bf16 v[60:63], v[236:239], v[170:173], v[60:63]
	v_mfma_f32_16x16x32_bf16 v[56:59], v[244:247], v[170:173], v[56:59]
	v_mfma_f32_16x16x32_bf16 v[44:47], v[236:239], v[178:181], v[44:47]
	v_mfma_f32_16x16x32_bf16 v[40:43], v[244:247], v[178:181], v[40:43]
	v_mfma_f32_16x16x32_bf16 v[28:31], v[236:239], v[190:193], v[28:31]
	v_mfma_f32_16x16x32_bf16 v[24:27], v[244:247], v[190:193], v[24:27]
	v_mfma_f32_16x16x32_bf16 v[12:15], v[236:239], v[198:201], v[12:15]
	v_mfma_f32_16x16x32_bf16 v[8:11], v[244:247], v[198:201], v[8:11]
	s_add_u32 s72, s72, 0x100
	s_addc_u32 s73, s73, 0
	s_add_u32 s50, s50, 0x100
	s_addc_u32 s51, s51, 0
	s_cmp_ge_u32 s74, s29
	s_mov_b32 s52, s74
	s_barrier
	s_cbranch_scc0 .LBB0_568
	s_branch .LBB0_570

; #define PG8_STAGE(bufoff, gbase, voff) do { _Pragma("unroll") for (int _i = 0; _i < 2; ++_i) \
;         __builtin_amdgcn_global_load_lds((const unsigned*)((const char*)(gbase) + (voff)[_i]), (LAS unsigned*)(lds + (bufoff) + ldsw + _i * 8192), 16, 0, 0); } while (0)
; #define PG8_LDA(dst, b, h) do { _Pragma("unroll") for (int m = 0; m < 4; ++m) _Pragma("unroll") for (int k = 0; k < 2; ++k) dst[m][k] = *(const LAS bf16x8*)(lds + PG8_SA(b, h) + aoff + m * 2048 + k * 1024); } while (0)
; #define PG8_LDB(dst, b, h) do { _Pragma("unroll") for (int n = 0; n < 2; ++n) _Pragma("unroll") for (int k = 0; k < 2; ++k) dst[n][k] = *(const LAS bf16x8*)(lds + PG8_SB(b, h) + boff + n * 2048 + k * 1024); } while (0)
; #define PG8_MMA(ai, bj, At, Bt) do { __builtin_amdgcn_s_setprio(1); _Pragma("unroll") for (int m = 0; m < 4; ++m) _Pragma("unroll") for (int n = 0; n < 2; ++n) _Pragma("unroll") for (int k = 0; k < 2; ++k) \
;         acc[ai][bj][m][n] = __builtin_amdgcn_mfma_f32_16x16x32_bf16(Bt[n][k], At[m][k], acc[ai][bj][m][n], 0, 0, 0); __builtin_amdgcn_s_setprio(0); } while (0)
; #define PG8_WAIT_L(n) asm volatile("s_waitcnt lgkmcnt(" #n ")" ::: "memory")
; #define PG8_BAR __builtin_amdgcn_s_barrier()
; #define PG8_SCHED __builtin_amdgcn_sched_barrier(0)
; template <class Epi>
; __device__ __forceinline__ void gemm_phase(LAS unsigned char* lds, const Gemm g, const StaticOrder& S, const Epi& E) {
;     ...
;             const bool last = (t == nt - 2);
;             const char* a1 = cA + (size_t)(t + 1) * kstep;
;             const char* a2 = last ? nA : cA + (size_t)(t + 2) * kstep; const char* b2 = last ? nB : cB + (size_t)(t + 2) * kstep;
;             const char* a3 = a2 + kstep; const char* b3 = b2 + kstep;
;             PG8_LDB(B0, 0, 0); PG8_SCHED; PG8_LDA(At, 0, 0); PG8_STAGE(PG8_SA(1, 1), a1 + hstep, voffA);
;             PG8_WAIT_L(8); PG8_BAR; PG8_WAIT_L(0); PG8_MMA(0, 0, At, B0); PG8_BAR; PG8_SCHED;
;             PG8_LDB(B1, 0, 1); PG8_STAGE(PG8_SB(0, 0), b2, voffB);
;             PG8_BAR; PG8_WAIT_L(0); PG8_MMA(0, 1, At, B1); PG8_BAR;
;             PG8_LDA(At, 0, 1); PG8_STAGE(PG8_SA(0, 0), a2, voffA);
;             PG8_BAR; PG8_WAIT_L(0); PG8_MMA(1, 0, At, B0); PG8_BAR; PG8_SCHED;
.LBB0_1489:
	s_add_i32 s30, s94, 2
	s_add_u32 s74, s72, 0x100
	s_addc_u32 s75, s73, 0
	s_add_i32 s31, 0, 0x10000
	v_add_u32_e32 v148, s31, v231
	ds_read_b128 v[136:139], v148
	ds_read_b128 v[140:143], v148 offset:1024
	ds_read_b128 v[144:147], v148 offset:2048
	ds_read_b128 v[148:151], v148 offset:3072
	s_cmp_eq_u32 s91, s94
	s_cselect_b32 s94, s69, s96
	s_cselect_b32 vcc_hi, s49, s75
	s_cselect_b32 vcc_lo, s61, s74
	s_cselect_b32 s95, s67, s97
	v_lshl_add_u64 v[190:191], s[72:73], 0, v[188:189]
	s_add_i32 m0, s78, 0xc000
	ds_read_b128 v[152:155], v233
	ds_read_b128 v[156:159], v233 offset:1024
	ds_read_b128 v[160:163], v233 offset:2048
	ds_read_b128 v[164:167], v233 offset:3072
	ds_read_b128 v[168:171], v233 offset:4096
	ds_read_b128 v[172:175], v233 offset:5120
	ds_read_b128 v[176:179], v233 offset:6144
	ds_read_b128 v[180:183], v233 offset:7168
	global_load_lds_dwordx4 v[190:191], off
	v_lshl_add_u64 v[190:191], s[72:73], 0, v[186:187]
	s_add_i32 m0, s78, 0xe000
	s_nop 0
	global_load_lds_dwordx4 v[190:191], off
	s_waitcnt lgkmcnt(8)
	s_barrier
	s_waitcnt lgkmcnt(0)
	v_mfma_f32_16x16x32_bf16 v[132:135], v[136:139], v[152:155], v[132:135]
	v_mfma_f32_16x16x32_bf16 v[128:131], v[144:147], v[152:155], v[128:131]
	v_mfma_f32_16x16x32_bf16 v[116:119], v[136:139], v[160:163], v[116:119]
	v_mfma_f32_16x16x32_bf16 v[112:115], v[144:147], v[160:163], v[112:115]
	v_mfma_f32_16x16x32_bf16 v[100:103], v[136:139], v[168:171], v[100:103]
	v_mfma_f32_16x16x32_bf16 v[96:99], v[144:147], v[168:171], v[96:99]
	v_mfma_f32_16x16x32_bf16 v[84:87], v[136:139], v[176:179], v[84:87]
	v_mfma_f32_16x16x32_bf16 v[80:83], v[144:147], v[176:179], v[80:83]
	v_mfma_f32_16x16x32_bf16 v[132:135], v[140:143], v[156:159], v[132:135]
	v_mfma_f32_16x16x32_bf16 v[128:131], v[148:151], v[156:159], v[128:131]
	v_mfma_f32_16x16x32_bf16 v[116:119], v[140:143], v[164:167], v[116:119]
	v_mfma_f32_16x16x32_bf16 v[112:115], v[148:151], v[164:167], v[112:115]
	v_mfma_f32_16x16x32_bf16 v[100:103], v[140:143], v[172:175], v[100:103]
	v_mfma_f32_16x16x32_bf16 v[96:99], v[148:151], v[172:175], v[96:99]
	v_mfma_f32_16x16x32_bf16 v[84:87], v[140:143], v[180:183], v[84:87]
	v_mfma_f32_16x16x32_bf16 v[80:83], v[148:151], v[180:183], v[80:83]
	s_barrier
	s_add_i32 s8, 0, 0x14000
	v_add_u32_e32 v218, s8, v231
	s_add_i32 s31, s31, s33
	ds_read_b128 v[190:193], v218
	ds_read_b128 v[194:197], v218 offset:1024
	ds_read_b128 v[198:201], v218 offset:2048
	ds_read_b128 v[234:237], v218 offset:3072
	v_lshl_add_u64 v[218:219], s[94:95], 0, v[0:1]
	s_mov_b32 m0, s31
	v_lshl_add_u64 v[238:239], s[94:95], 0, v[2:3]
	global_load_lds_dwordx4 v[218:219], off
	s_add_i32 m0, s31, 0x2000
	s_nop 0
	global_load_lds_dwordx4 v[238:239], off
	s_barrier
	s_waitcnt lgkmcnt(0)
	v_mfma_f32_16x16x32_bf16 v[124:127], v[190:193], v[152:155], v[124:127]
	v_mfma_f32_16x16x32_bf16 v[120:123], v[198:201], v[152:155], v[120:123]
	v_mfma_f32_16x16x32_bf16 v[108:111], v[190:193], v[160:163], v[108:111]
	v_mfma_f32_16x16x32_bf16 v[104:107], v[198:201], v[160:163], v[104:107]
	v_mfma_f32_16x16x32_bf16 v[92:95], v[190:193], v[168:171], v[92:95]
	v_mfma_f32_16x16x32_bf16 v[88:91], v[198:201], v[168:171], v[88:91]
	v_mfma_f32_16x16x32_bf16 v[76:79], v[190:193], v[176:179], v[76:79]
	v_mfma_f32_16x16x32_bf16 v[72:75], v[198:201], v[176:179], v[72:75]
	v_mfma_f32_16x16x32_bf16 v[124:127], v[194:197], v[156:159], v[124:127]
	v_mfma_f32_16x16x32_bf16 v[120:123], v[234:237], v[156:159], v[120:123]
	v_mfma_f32_16x16x32_bf16 v[108:111], v[194:197], v[164:167], v[108:111]
	v_mfma_f32_16x16x32_bf16 v[104:107], v[234:237], v[164:167], v[104:107]
	v_mfma_f32_16x16x32_bf16 v[92:95], v[194:197], v[172:175], v[92:95]
	v_mfma_f32_16x16x32_bf16 v[88:91], v[234:237], v[172:175], v[88:91]
	v_mfma_f32_16x16x32_bf16 v[76:79], v[194:197], v[180:183], v[76:79]
	v_mfma_f32_16x16x32_bf16 v[72:75], v[234:237], v[180:183], v[72:75]
	s_mov_b32 m0, s78
	v_lshl_add_u64 v[240:241], vcc, 0, v[0:1]
	s_barrier
	ds_read_b128 v[152:155], v233 offset:16384
	ds_read_b128 v[156:159], v233 offset:17408
	ds_read_b128 v[160:163], v233 offset:18432
	ds_read_b128 v[164:167], v233 offset:19456
	ds_read_b128 v[168:171], v233 offset:20480
	ds_read_b128 v[172:175], v233 offset:21504
	ds_read_b128 v[176:179], v233 offset:22528
	ds_read_b128 v[180:183], v233 offset:23552
	global_load_lds_dwordx4 v[240:241], off
	v_lshl_add_u64 v[242:243], vcc, 0, v[2:3]
	s_mov_b32 m0, s18
	s_nop 0
	global_load_lds_dwordx4 v[242:243], off
	s_barrier
	s_waitcnt lgkmcnt(0)
	v_mfma_f32_16x16x32_bf16 v[68:71], v[136:139], v[152:155], v[68:71]
	v_mfma_f32_16x16x32_bf16 v[64:67], v[144:147], v[152:155], v[64:67]
	v_mfma_f32_16x16x32_bf16 v[52:55], v[136:139], v[160:163], v[52:55]
	v_mfma_f32_16x16x32_bf16 v[48:51], v[144:147], v[160:163], v[48:51]
	v_mfma_f32_16x16x32_bf16 v[36:39], v[136:139], v[168:171], v[36:39]
	v_mfma_f32_16x16x32_bf16 v[32:35], v[144:147], v[168:171], v[32:35]
	v_mfma_f32_16x16x32_bf16 v[20:23], v[136:139], v[176:179], v[20:23]
	v_mfma_f32_16x16x32_bf16 v[16:19], v[144:147], v[176:179], v[16:19]
	v_mfma_f32_16x16x32_bf16 v[68:71], v[140:143], v[156:159], v[68:71]
	v_mfma_f32_16x16x32_bf16 v[64:67], v[148:151], v[156:159], v[64:67]
	v_mfma_f32_16x16x32_bf16 v[52:55], v[140:143], v[164:167], v[52:55]
	v_mfma_f32_16x16x32_bf16 v[48:51], v[148:151], v[164:167], v[48:51]
	v_mfma_f32_16x16x32_bf16 v[36:39], v[140:143], v[172:175], v[36:39]
	v_mfma_f32_16x16x32_bf16 v[32:35], v[148:151], v[172:175], v[32:35]
	v_mfma_f32_16x16x32_bf16 v[20:23], v[140:143], v[180:183], v[20:23]
	v_mfma_f32_16x16x32_bf16 v[16:19], v[148:151], v[180:183], v[16:19]
	s_barrier
; #define PG8_STAGE(bufoff, gbase, voff) do { _Pragma("unroll") for (int _i = 0; _i < 2; ++_i) \
;         __builtin_amdgcn_global_load_lds((const unsigned*)((const char*)(gbase) + (voff)[_i]), (LAS unsigned*)(lds + (bufoff) + ldsw + _i * 8192), 16, 0, 0); } while (0)
; #define PG8_LDA(dst, b, h) do { _Pragma("unroll") for (int m = 0; m < 4; ++m) _Pragma("unroll") for (int k = 0; k < 2; ++k) dst[m][k] = *(const LAS bf16x8*)(lds + PG8_SA(b, h) + aoff + m * 2048 + k * 1024); } while (0)
; #define PG8_LDB(dst, b, h) do { _Pragma("unroll") for (int n = 0; n < 2; ++n) _Pragma("unroll") for (int k = 0; k < 2; ++k) dst[n][k] = *(const LAS bf16x8*)(lds + PG8_SB(b, h) + boff + n * 2048 + k * 1024); } while (0)
; #define PG8_MMA(ai, bj, At, Bt) do { __builtin_amdgcn_s_setprio(1); _Pragma("unroll") for (int m = 0; m < 4; ++m) _Pragma("unroll") for (int n = 0; n < 2; ++n) _Pragma("unroll") for (int k = 0; k < 2; ++k) \
;         acc[ai][bj][m][n] = __builtin_amdgcn_mfma_f32_16x16x32_bf16(Bt[n][k], At[m][k], acc[ai][bj][m][n], 0, 0, 0); __builtin_amdgcn_s_setprio(0); } while (0)
; #define PG8_WAIT_V(n) asm volatile("s_waitcnt vmcnt(" #n ")" ::: "memory")
; #define PG8_WAIT_L(n) asm volatile("s_waitcnt lgkmcnt(" #n ")" ::: "memory")
; #define PG8_BAR __builtin_amdgcn_s_barrier()
; #define PG8_SCHED __builtin_amdgcn_sched_barrier(0)
; template <class Epi>
; __device__ __forceinline__ void gemm_phase(LAS unsigned char* lds, const Gemm g, const StaticOrder& S, const Epi& E) {
;     ...
;             PG8_STAGE(PG8_SB(0, 1), b2 + hstep, voffB);
;             PG8_WAIT_V(6); PG8_BAR; PG8_MMA(1, 1, At, B1); PG8_BAR;
;             PG8_LDB(B0, 1, 0); PG8_SCHED; PG8_LDA(At, 1, 0); PG8_STAGE(PG8_SA(0, 1), a2 + hstep, voffA);
;             PG8_WAIT_L(8); PG8_BAR; PG8_WAIT_L(0); PG8_MMA(0, 0, At, B0); PG8_BAR; PG8_SCHED;
;             PG8_LDB(B1, 1, 1); PG8_STAGE(PG8_SB(1, 0), b3, voffB);
;             PG8_BAR; PG8_WAIT_L(0); PG8_MMA(0, 1, At, B1); PG8_BAR;
	s_add_u32 s72, s94, 0x40000
	s_addc_u32 s73, s95, 0
	s_add_i32 s8, s8, s33
	v_lshl_add_u64 v[136:137], s[72:73], 0, v[0:1]
	s_mov_b32 m0, s8
	s_nop 0
	global_load_lds_dwordx4 v[136:137], off
	v_lshl_add_u64 v[136:137], s[72:73], 0, v[2:3]
	s_add_i32 m0, s8, 0x2000
	s_nop 0
	global_load_lds_dwordx4 v[136:137], off
	s_waitcnt vmcnt(6)
	s_barrier
	v_mfma_f32_16x16x32_bf16 v[60:63], v[190:193], v[152:155], v[60:63]
	v_mfma_f32_16x16x32_bf16 v[56:59], v[198:201], v[152:155], v[56:59]
	v_mfma_f32_16x16x32_bf16 v[44:47], v[190:193], v[160:163], v[44:47]
	v_mfma_f32_16x16x32_bf16 v[40:43], v[198:201], v[160:163], v[40:43]
	v_mfma_f32_16x16x32_bf16 v[28:31], v[190:193], v[168:171], v[28:31]
	v_mfma_f32_16x16x32_bf16 v[24:27], v[198:201], v[168:171], v[24:27]
	v_mfma_f32_16x16x32_bf16 v[12:15], v[190:193], v[176:179], v[12:15]
	v_mfma_f32_16x16x32_bf16 v[8:11], v[198:201], v[176:179], v[8:11]
	v_mfma_f32_16x16x32_bf16 v[60:63], v[194:197], v[156:159], v[60:63]
	v_mfma_f32_16x16x32_bf16 v[56:59], v[234:237], v[156:159], v[56:59]
	v_mfma_f32_16x16x32_bf16 v[44:47], v[194:197], v[164:167], v[44:47]
	v_mfma_f32_16x16x32_bf16 v[40:43], v[234:237], v[164:167], v[40:43]
	v_mfma_f32_16x16x32_bf16 v[28:31], v[194:197], v[172:175], v[28:31]
	v_mfma_f32_16x16x32_bf16 v[24:27], v[234:237], v[172:175], v[24:27]
	v_mfma_f32_16x16x32_bf16 v[12:15], v[194:197], v[180:183], v[12:15]
	v_mfma_f32_16x16x32_bf16 v[8:11], v[234:237], v[180:183], v[8:11]
	s_add_i32 s8, 0, 0x18000
	v_add_u32_e32 v148, s8, v231
	s_barrier
	ds_read_b128 v[136:139], v148
	ds_read_b128 v[140:143], v148 offset:1024
	ds_read_b128 v[144:147], v148 offset:2048
	ds_read_b128 v[148:151], v148 offset:3072
	s_add_u32 s72, vcc_lo, 0x40000
	s_addc_u32 s73, vcc_hi, 0
	s_mov_b32 m0, s19
	v_lshl_add_u64 v[190:191], s[72:73], 0, v[0:1]
	ds_read_b128 v[152:155], v233 offset:32768
	ds_read_b128 v[156:159], v233 offset:33792
	ds_read_b128 v[160:163], v233 offset:34816
	ds_read_b128 v[164:167], v233 offset:35840
	ds_read_b128 v[168:171], v233 offset:36864
	ds_read_b128 v[172:175], v233 offset:37888
	ds_read_b128 v[176:179], v233 offset:38912
	ds_read_b128 v[180:183], v233 offset:39936
	global_load_lds_dwordx4 v[190:191], off
	v_lshl_add_u64 v[190:191], s[72:73], 0, v[2:3]
	s_mov_b32 m0, s20
	s_nop 0
	global_load_lds_dwordx4 v[190:191], off
	s_waitcnt lgkmcnt(8)
	s_barrier
	s_waitcnt lgkmcnt(0)
	v_mfma_f32_16x16x32_bf16 v[132:135], v[136:139], v[152:155], v[132:135]
	v_mfma_f32_16x16x32_bf16 v[128:131], v[144:147], v[152:155], v[128:131]
	v_mfma_f32_16x16x32_bf16 v[116:119], v[136:139], v[160:163], v[116:119]
	v_mfma_f32_16x16x32_bf16 v[112:115], v[144:147], v[160:163], v[112:115]
	v_mfma_f32_16x16x32_bf16 v[100:103], v[136:139], v[168:171], v[100:103]
	v_mfma_f32_16x16x32_bf16 v[96:99], v[144:147], v[168:171], v[96:99]
	v_mfma_f32_16x16x32_bf16 v[84:87], v[136:139], v[176:179], v[84:87]
	v_mfma_f32_16x16x32_bf16 v[80:83], v[144:147], v[176:179], v[80:83]
	v_mfma_f32_16x16x32_bf16 v[132:135], v[140:143], v[156:159], v[132:135]
	v_mfma_f32_16x16x32_bf16 v[128:131], v[148:151], v[156:159], v[128:131]
	v_mfma_f32_16x16x32_bf16 v[116:119], v[140:143], v[164:167], v[116:119]
	v_mfma_f32_16x16x32_bf16 v[112:115], v[148:151], v[164:167], v[112:115]
	v_mfma_f32_16x16x32_bf16 v[100:103], v[140:143], v[172:175], v[100:103]
	v_mfma_f32_16x16x32_bf16 v[96:99], v[148:151], v[172:175], v[96:99]
	v_mfma_f32_16x16x32_bf16 v[84:87], v[140:143], v[180:183], v[84:87]
	v_mfma_f32_16x16x32_bf16 v[80:83], v[148:151], v[180:183], v[80:83]
	s_barrier
	s_add_i32 s31, 0, 0x1c000
	s_add_i32 s8, s8, s33
	v_add_u32_e32 v234, s31, v231
	v_lshl_add_u64 v[218:219], v[218:219], 0, s[12:13]
	s_mov_b32 m0, s8
	ds_read_b128 v[190:193], v234
	ds_read_b128 v[194:197], v234 offset:1024
	ds_read_b128 v[198:201], v234 offset:2048
	ds_read_b128 v[234:237], v234 offset:3072
	global_load_lds_dwordx4 v[218:219], off
	v_lshl_add_u64 v[218:219], v[238:239], 0, s[12:13]
	s_add_i32 m0, s8, 0x2000
	s_nop 0
	global_load_lds_dwordx4 v[218:219], off
	s_barrier
; #define PG8_STAGE(bufoff, gbase, voff) do { _Pragma("unroll") for (int _i = 0; _i < 2; ++_i) \
;         __builtin_amdgcn_global_load_lds((const unsigned*)((const char*)(gbase) + (voff)[_i]), (LAS unsigned*)(lds + (bufoff) + ldsw + _i * 8192), 16, 0, 0); } while (0)
; #define PG8_LDA(dst, b, h) do { _Pragma("unroll") for (int m = 0; m < 4; ++m) _Pragma("unroll") for (int k = 0; k < 2; ++k) dst[m][k] = *(const LAS bf16x8*)(lds + PG8_SA(b, h) + aoff + m * 2048 + k * 1024); } while (0)
; #define PG8_MMA(ai, bj, At, Bt) do { __builtin_amdgcn_s_setprio(1); _Pragma("unroll") for (int m = 0; m < 4; ++m) _Pragma("unroll") for (int n = 0; n < 2; ++n) _Pragma("unroll") for (int k = 0; k < 2; ++k) \
;         acc[ai][bj][m][n] = __builtin_amdgcn_mfma_f32_16x16x32_bf16(Bt[n][k], At[m][k], acc[ai][bj][m][n], 0, 0, 0); __builtin_amdgcn_s_setprio(0); } while (0)
; #define PG8_WAIT_V(n) asm volatile("s_waitcnt vmcnt(" #n ")" ::: "memory")
; #define PG8_WAIT_L(n) asm volatile("s_waitcnt lgkmcnt(" #n ")" ::: "memory")
; #define PG8_BAR __builtin_amdgcn_s_barrier()
; #define PG8_SCHED __builtin_amdgcn_sched_barrier(0)
; template <class Epi>
; __device__ __forceinline__ void gemm_phase(LAS unsigned char* lds, const Gemm g, const StaticOrder& S, const Epi& E) {
;     ...
;             PG8_BAR; PG8_WAIT_L(0); PG8_MMA(0, 1, At, B1); PG8_BAR;
;             PG8_LDA(At, 1, 1); PG8_STAGE(PG8_SA(1, 0), a3, voffA);
;             PG8_BAR; PG8_WAIT_L(0); PG8_MMA(1, 0, At, B0); PG8_BAR; PG8_SCHED;
;             PG8_STAGE(PG8_SB(1, 1), b3 + hstep, voffB);
;             PG8_WAIT_V(6); PG8_BAR; PG8_MMA(1, 1, At, B1); PG8_BAR;
	s_waitcnt lgkmcnt(0)
	v_mfma_f32_16x16x32_bf16 v[124:127], v[190:193], v[152:155], v[124:127]
	v_mfma_f32_16x16x32_bf16 v[120:123], v[198:201], v[152:155], v[120:123]
	v_mfma_f32_16x16x32_bf16 v[108:111], v[190:193], v[160:163], v[108:111]
	v_mfma_f32_16x16x32_bf16 v[104:107], v[198:201], v[160:163], v[104:107]
	v_mfma_f32_16x16x32_bf16 v[92:95], v[190:193], v[168:171], v[92:95]
	v_mfma_f32_16x16x32_bf16 v[88:91], v[198:201], v[168:171], v[88:91]
	v_mfma_f32_16x16x32_bf16 v[76:79], v[190:193], v[176:179], v[76:79]
	v_mfma_f32_16x16x32_bf16 v[72:75], v[198:201], v[176:179], v[72:75]
	v_mfma_f32_16x16x32_bf16 v[124:127], v[194:197], v[156:159], v[124:127]
	v_mfma_f32_16x16x32_bf16 v[120:123], v[234:237], v[156:159], v[120:123]
	v_mfma_f32_16x16x32_bf16 v[108:111], v[194:197], v[164:167], v[108:111]
	v_mfma_f32_16x16x32_bf16 v[104:107], v[234:237], v[164:167], v[104:107]
	v_mfma_f32_16x16x32_bf16 v[92:95], v[194:197], v[172:175], v[92:95]
	v_mfma_f32_16x16x32_bf16 v[88:91], v[234:237], v[172:175], v[88:91]
	v_mfma_f32_16x16x32_bf16 v[76:79], v[194:197], v[180:183], v[76:79]
	v_mfma_f32_16x16x32_bf16 v[72:75], v[234:237], v[180:183], v[72:75]
	s_mov_b32 m0, s24
	v_lshl_add_u64 v[218:219], v[240:241], 0, s[12:13]
	s_barrier
	ds_read_b128 v[152:155], v233 offset:49152
	ds_read_b128 v[156:159], v233 offset:50176
	ds_read_b128 v[160:163], v233 offset:51200
	ds_read_b128 v[164:167], v233 offset:52224
	ds_read_b128 v[168:171], v233 offset:53248
	ds_read_b128 v[172:175], v233 offset:54272
	ds_read_b128 v[176:179], v233 offset:55296
	ds_read_b128 v[180:183], v233 offset:56320
	global_load_lds_dwordx4 v[218:219], off
	v_lshl_add_u64 v[218:219], v[242:243], 0, s[12:13]
	s_mov_b32 m0, s25
	s_nop 0
	global_load_lds_dwordx4 v[218:219], off
	s_barrier
	s_waitcnt lgkmcnt(0)
	v_mfma_f32_16x16x32_bf16 v[68:71], v[136:139], v[152:155], v[68:71]
	v_mfma_f32_16x16x32_bf16 v[64:67], v[144:147], v[152:155], v[64:67]
	v_mfma_f32_16x16x32_bf16 v[52:55], v[136:139], v[160:163], v[52:55]
	v_mfma_f32_16x16x32_bf16 v[48:51], v[144:147], v[160:163], v[48:51]
	v_mfma_f32_16x16x32_bf16 v[36:39], v[136:139], v[168:171], v[36:39]
	v_mfma_f32_16x16x32_bf16 v[32:35], v[144:147], v[168:171], v[32:35]
	v_mfma_f32_16x16x32_bf16 v[20:23], v[136:139], v[176:179], v[20:23]
	v_mfma_f32_16x16x32_bf16 v[16:19], v[144:147], v[176:179], v[16:19]
	v_mfma_f32_16x16x32_bf16 v[68:71], v[140:143], v[156:159], v[68:71]
	v_mfma_f32_16x16x32_bf16 v[64:67], v[148:151], v[156:159], v[64:67]
	v_mfma_f32_16x16x32_bf16 v[52:55], v[140:143], v[164:167], v[52:55]
	v_mfma_f32_16x16x32_bf16 v[48:51], v[148:151], v[164:167], v[48:51]
	v_mfma_f32_16x16x32_bf16 v[36:39], v[140:143], v[172:175], v[36:39]
	v_mfma_f32_16x16x32_bf16 v[32:35], v[148:151], v[172:175], v[32:35]
	v_mfma_f32_16x16x32_bf16 v[20:23], v[140:143], v[180:183], v[20:23]
	v_mfma_f32_16x16x32_bf16 v[16:19], v[148:151], v[180:183], v[16:19]
	s_barrier
	s_add_u32 s72, s94, 0x40080
	s_addc_u32 s73, s95, 0
	s_add_i32 s8, s31, s33
	v_lshl_add_u64 v[136:137], s[72:73], 0, v[0:1]
	s_mov_b32 m0, s8
	s_nop 0
	global_load_lds_dwordx4 v[136:137], off
	v_lshl_add_u64 v[136:137], s[72:73], 0, v[2:3]
	s_add_i32 m0, s8, 0x2000
	s_nop 0
	global_load_lds_dwordx4 v[136:137], off
	s_waitcnt vmcnt(6)
	s_barrier
	v_mfma_f32_16x16x32_bf16 v[60:63], v[190:193], v[152:155], v[60:63]
	v_mfma_f32_16x16x32_bf16 v[56:59], v[198:201], v[152:155], v[56:59]
	v_mfma_f32_16x16x32_bf16 v[44:47], v[190:193], v[160:163], v[44:47]
	v_mfma_f32_16x16x32_bf16 v[40:43], v[198:201], v[160:163], v[40:43]
	v_mfma_f32_16x16x32_bf16 v[28:31], v[190:193], v[168:171], v[28:31]
	v_mfma_f32_16x16x32_bf16 v[24:27], v[198:201], v[168:171], v[24:27]
	v_mfma_f32_16x16x32_bf16 v[12:15], v[190:193], v[176:179], v[12:15]
	v_mfma_f32_16x16x32_bf16 v[8:11], v[198:201], v[176:179], v[8:11]
	v_mfma_f32_16x16x32_bf16 v[60:63], v[194:197], v[156:159], v[60:63]
	v_mfma_f32_16x16x32_bf16 v[56:59], v[234:237], v[156:159], v[56:59]
	v_mfma_f32_16x16x32_bf16 v[44:47], v[194:197], v[164:167], v[44:47]
	v_mfma_f32_16x16x32_bf16 v[40:43], v[234:237], v[164:167], v[40:43]
	v_mfma_f32_16x16x32_bf16 v[28:31], v[194:197], v[172:175], v[28:31]
	v_mfma_f32_16x16x32_bf16 v[24:27], v[234:237], v[172:175], v[24:27]
	v_mfma_f32_16x16x32_bf16 v[12:15], v[194:197], v[180:183], v[12:15]
	v_mfma_f32_16x16x32_bf16 v[8:11], v[234:237], v[180:183], v[8:11]
	s_add_u32 s96, s96, 0x100
	s_addc_u32 s97, s97, 0
	s_cmp_ge_i32 s30, s90
	s_mov_b64 s[72:73], s[74:75]
	s_mov_b32 s94, s30
	s_barrier
	s_cbranch_scc0 .LBB0_1489
	s_mov_b64 s[96:97], s[50:51]
	s_branch .LBB0_1492

; #define PG8_STAGE(bufoff, gbase, voff) do { _Pragma("unroll") for (int _i = 0; _i < 2; ++_i) \
;         __builtin_amdgcn_global_load_lds((const unsigned*)((const char*)(gbase) + (voff)[_i]), (LAS unsigned*)(lds + (bufoff) + ldsw + _i * 8192), 16, 0, 0); } while (0)
; #define PG8_LDA(dst, b, h) do { _Pragma("unroll") for (int m = 0; m < 4; ++m) _Pragma("unroll") for (int k = 0; k < 2; ++k) dst[m][k] = *(const LAS bf16x8*)(lds + PG8_SA(b, h) + aoff + m * 2048 + k * 1024); } while (0)
; #define PG8_LDB(dst, b, h) do { _Pragma("unroll") for (int n = 0; n < 2; ++n) _Pragma("unroll") for (int k = 0; k < 2; ++k) dst[n][k] = *(const LAS bf16x8*)(lds + PG8_SB(b, h) + boff + n * 2048 + k * 1024); } while (0)
; #define PG8_MMA(ai, bj, At, Bt) do { __builtin_amdgcn_s_setprio(1); _Pragma("unroll") for (int m = 0; m < 4; ++m) _Pragma("unroll") for (int n = 0; n < 2; ++n) _Pragma("unroll") for (int k = 0; k < 2; ++k) \
;         acc[ai][bj][m][n] = __builtin_amdgcn_mfma_f32_16x16x32_bf16(Bt[n][k], At[m][k], acc[ai][bj][m][n], 0, 0, 0); __builtin_amdgcn_s_setprio(0); } while (0)
; #define PG8_WAIT_L(n) asm volatile("s_waitcnt lgkmcnt(" #n ")" ::: "memory")
; #define PG8_BAR __builtin_amdgcn_s_barrier()
; #define PG8_SCHED __builtin_amdgcn_sched_barrier(0)
; template <class Epi>
; __device__ __forceinline__ void gemm_phase(LAS unsigned char* lds, const Gemm g, const StaticOrder& S, const Epi& E) {
;     ...
;             const bool last = (t == nt - 2);
;             const char* a1 = cA + (size_t)(t + 1) * kstep;
;             const char* a2 = last ? nA : cA + (size_t)(t + 2) * kstep; const char* b2 = last ? nB : cB + (size_t)(t + 2) * kstep;
;             const char* a3 = a2 + kstep; const char* b3 = b2 + kstep;
;             PG8_LDB(B0, 0, 0); PG8_SCHED; PG8_LDA(At, 0, 0); PG8_STAGE(PG8_SA(1, 1), a1 + hstep, voffA);
;             PG8_WAIT_L(8); PG8_BAR; PG8_WAIT_L(0); PG8_MMA(0, 0, At, B0); PG8_BAR; PG8_SCHED;
;             PG8_LDB(B1, 0, 1); PG8_STAGE(PG8_SB(0, 0), b2, voffB);
;             PG8_BAR; PG8_WAIT_L(0); PG8_MMA(0, 1, At, B1); PG8_BAR;
;             PG8_LDA(At, 0, 1); PG8_STAGE(PG8_SA(0, 0), a2, voffA);
;             PG8_BAR; PG8_WAIT_L(0); PG8_MMA(1, 0, At, B0); PG8_BAR; PG8_SCHED;
.LBB0_1766:
	s_add_i32 s33, s29, 2
	s_add_u32 s8, s58, 0xfffc0080
	s_addc_u32 s45, s59, -1
	s_add_i32 s47, 0, 0x10000
	v_add_u32_e32 v160, s47, v145
	ds_read_b128 v[148:151], v160
	ds_read_b128 v[152:155], v160 offset:1024
	ds_read_b128 v[156:159], v160 offset:2048
	ds_read_b128 v[160:163], v160 offset:3072
	s_cmp_eq_u32 s23, s29
	s_cselect_b32 s63, s4, s45
	s_cselect_b32 s62, s5, s8
	s_cselect_b32 s61, s21, s25
	s_cselect_b32 s60, s22, s24
	v_lshl_add_u64 v[198:199], s[58:59], 0, v[142:143]
	s_add_i32 m0, s57, 0xc000
	ds_read_b128 v[164:167], v147
	ds_read_b128 v[168:171], v147 offset:1024
	ds_read_b128 v[172:175], v147 offset:2048
	ds_read_b128 v[176:179], v147 offset:3072
	ds_read_b128 v[180:183], v147 offset:4096
	ds_read_b128 v[186:189], v147 offset:5120
	ds_read_b128 v[190:193], v147 offset:6144
	ds_read_b128 v[194:197], v147 offset:7168
	global_load_lds_dwordx4 v[198:199], off
	v_lshl_add_u64 v[198:199], s[58:59], 0, v[140:141]
	s_add_i32 m0, s57, 0xe000
	s_nop 0
	global_load_lds_dwordx4 v[198:199], off
	s_waitcnt lgkmcnt(8)
	s_barrier
	s_waitcnt lgkmcnt(0)
	v_mfma_f32_16x16x32_bf16 v[132:135], v[148:151], v[164:167], v[132:135]
	v_mfma_f32_16x16x32_bf16 v[124:127], v[156:159], v[164:167], v[124:127]
	v_mfma_f32_16x16x32_bf16 v[116:119], v[148:151], v[172:175], v[116:119]
	v_mfma_f32_16x16x32_bf16 v[108:111], v[156:159], v[172:175], v[108:111]
	v_mfma_f32_16x16x32_bf16 v[100:103], v[148:151], v[180:183], v[100:103]
	v_mfma_f32_16x16x32_bf16 v[92:95], v[156:159], v[180:183], v[92:95]
	v_mfma_f32_16x16x32_bf16 v[84:87], v[148:151], v[190:193], v[84:87]
	v_mfma_f32_16x16x32_bf16 v[76:79], v[156:159], v[190:193], v[76:79]
	v_mfma_f32_16x16x32_bf16 v[132:135], v[152:155], v[168:171], v[132:135]
	v_mfma_f32_16x16x32_bf16 v[124:127], v[160:163], v[168:171], v[124:127]
	v_mfma_f32_16x16x32_bf16 v[116:119], v[152:155], v[176:179], v[116:119]
	v_mfma_f32_16x16x32_bf16 v[108:111], v[160:163], v[176:179], v[108:111]
	v_mfma_f32_16x16x32_bf16 v[100:103], v[152:155], v[186:189], v[100:103]
	v_mfma_f32_16x16x32_bf16 v[92:95], v[160:163], v[186:189], v[92:95]
	v_mfma_f32_16x16x32_bf16 v[84:87], v[152:155], v[194:197], v[84:87]
	v_mfma_f32_16x16x32_bf16 v[76:79], v[160:163], v[194:197], v[76:79]
	s_barrier
	s_add_i32 s8, 0, 0x14000
	s_add_i32 s29, s47, s66
	v_add_u32_e32 v185, s8, v145
	v_lshl_add_u64 v[218:219], s[60:61], 0, v[0:1]
	s_mov_b32 m0, s29
	ds_read_b128 v[198:201], v185
	ds_read_b128 v[232:235], v185 offset:1024
	ds_read_b128 v[236:239], v185 offset:2048
	ds_read_b128 v[240:243], v185 offset:3072
	global_load_lds_dwordx4 v[218:219], off
	v_lshl_add_u64 v[244:245], s[60:61], 0, v[2:3]
	s_add_i32 m0, s29, 0x2000
	s_nop 0
	global_load_lds_dwordx4 v[244:245], off
	s_barrier
	s_waitcnt lgkmcnt(0)
	v_mfma_f32_16x16x32_bf16 v[128:131], v[198:201], v[164:167], v[128:131]
	v_mfma_f32_16x16x32_bf16 v[120:123], v[236:239], v[164:167], v[120:123]
	v_mfma_f32_16x16x32_bf16 v[112:115], v[198:201], v[172:175], v[112:115]
	v_mfma_f32_16x16x32_bf16 v[104:107], v[236:239], v[172:175], v[104:107]
	v_mfma_f32_16x16x32_bf16 v[96:99], v[198:201], v[180:183], v[96:99]
	v_mfma_f32_16x16x32_bf16 v[88:91], v[236:239], v[180:183], v[88:91]
	v_mfma_f32_16x16x32_bf16 v[80:83], v[198:201], v[190:193], v[80:83]
	v_mfma_f32_16x16x32_bf16 v[72:75], v[236:239], v[190:193], v[72:75]
	v_mfma_f32_16x16x32_bf16 v[128:131], v[232:235], v[168:171], v[128:131]
	v_mfma_f32_16x16x32_bf16 v[120:123], v[240:243], v[168:171], v[120:123]
	v_mfma_f32_16x16x32_bf16 v[112:115], v[232:235], v[176:179], v[112:115]
	v_mfma_f32_16x16x32_bf16 v[104:107], v[240:243], v[176:179], v[104:107]
	v_mfma_f32_16x16x32_bf16 v[96:99], v[232:235], v[186:189], v[96:99]
	v_mfma_f32_16x16x32_bf16 v[88:91], v[240:243], v[186:189], v[88:91]
	v_mfma_f32_16x16x32_bf16 v[80:83], v[232:235], v[194:197], v[80:83]
	v_mfma_f32_16x16x32_bf16 v[72:75], v[240:243], v[194:197], v[72:75]
	s_mov_b32 m0, s57
	v_lshl_add_u64 v[246:247], s[62:63], 0, v[138:139]
	s_barrier
	ds_read_b128 v[164:167], v147 offset:16384
	ds_read_b128 v[168:171], v147 offset:17408
	ds_read_b128 v[172:175], v147 offset:18432
	ds_read_b128 v[176:179], v147 offset:19456
	ds_read_b128 v[180:183], v147 offset:20480
	ds_read_b128 v[186:189], v147 offset:21504
	ds_read_b128 v[190:193], v147 offset:22528
	ds_read_b128 v[194:197], v147 offset:23552
	global_load_lds_dwordx4 v[246:247], off
	v_lshl_add_u64 v[248:249], s[62:63], 0, v[136:137]
	s_mov_b32 m0, s67
	s_nop 0
	global_load_lds_dwordx4 v[248:249], off
	s_barrier
	s_waitcnt lgkmcnt(0)
	v_mfma_f32_16x16x32_bf16 v[68:71], v[148:151], v[164:167], v[68:71]
	v_mfma_f32_16x16x32_bf16 v[60:63], v[156:159], v[164:167], v[60:63]
	v_mfma_f32_16x16x32_bf16 v[52:55], v[148:151], v[172:175], v[52:55]
	v_mfma_f32_16x16x32_bf16 v[44:47], v[156:159], v[172:175], v[44:47]
	v_mfma_f32_16x16x32_bf16 v[36:39], v[148:151], v[180:183], v[36:39]
	v_mfma_f32_16x16x32_bf16 v[28:31], v[156:159], v[180:183], v[28:31]
	v_mfma_f32_16x16x32_bf16 v[20:23], v[148:151], v[190:193], v[20:23]
	v_mfma_f32_16x16x32_bf16 v[12:15], v[156:159], v[190:193], v[12:15]
	v_mfma_f32_16x16x32_bf16 v[68:71], v[152:155], v[168:171], v[68:71]
	v_mfma_f32_16x16x32_bf16 v[60:63], v[160:163], v[168:171], v[60:63]
	v_mfma_f32_16x16x32_bf16 v[52:55], v[152:155], v[176:179], v[52:55]
	v_mfma_f32_16x16x32_bf16 v[44:47], v[160:163], v[176:179], v[44:47]
	v_mfma_f32_16x16x32_bf16 v[36:39], v[152:155], v[186:189], v[36:39]
	v_mfma_f32_16x16x32_bf16 v[28:31], v[160:163], v[186:189], v[28:31]
	v_mfma_f32_16x16x32_bf16 v[20:23], v[152:155], v[194:197], v[20:23]
	v_mfma_f32_16x16x32_bf16 v[12:15], v[160:163], v[194:197], v[12:15]
	s_barrier
; #define PG8_STAGE(bufoff, gbase, voff) do { _Pragma("unroll") for (int _i = 0; _i < 2; ++_i) \
;         __builtin_amdgcn_global_load_lds((const unsigned*)((const char*)(gbase) + (voff)[_i]), (LAS unsigned*)(lds + (bufoff) + ldsw + _i * 8192), 16, 0, 0); } while (0)
; #define PG8_LDA(dst, b, h) do { _Pragma("unroll") for (int m = 0; m < 4; ++m) _Pragma("unroll") for (int k = 0; k < 2; ++k) dst[m][k] = *(const LAS bf16x8*)(lds + PG8_SA(b, h) + aoff + m * 2048 + k * 1024); } while (0)
; #define PG8_LDB(dst, b, h) do { _Pragma("unroll") for (int n = 0; n < 2; ++n) _Pragma("unroll") for (int k = 0; k < 2; ++k) dst[n][k] = *(const LAS bf16x8*)(lds + PG8_SB(b, h) + boff + n * 2048 + k * 1024); } while (0)
; #define PG8_MMA(ai, bj, At, Bt) do { __builtin_amdgcn_s_setprio(1); _Pragma("unroll") for (int m = 0; m < 4; ++m) _Pragma("unroll") for (int n = 0; n < 2; ++n) _Pragma("unroll") for (int k = 0; k < 2; ++k) \
;         acc[ai][bj][m][n] = __builtin_amdgcn_mfma_f32_16x16x32_bf16(Bt[n][k], At[m][k], acc[ai][bj][m][n], 0, 0, 0); __builtin_amdgcn_s_setprio(0); } while (0)
; #define PG8_WAIT_V(n) asm volatile("s_waitcnt vmcnt(" #n ")" ::: "memory")
; #define PG8_WAIT_L(n) asm volatile("s_waitcnt lgkmcnt(" #n ")" ::: "memory")
; #define PG8_BAR __builtin_amdgcn_s_barrier()
; #define PG8_SCHED __builtin_amdgcn_sched_barrier(0)
; template <class Epi>
; __device__ __forceinline__ void gemm_phase(LAS unsigned char* lds, const Gemm g, const StaticOrder& S, const Epi& E) {
;     ...
;             PG8_STAGE(PG8_SB(0, 1), b2 + hstep, voffB);
;             PG8_WAIT_V(6); PG8_BAR; PG8_MMA(1, 1, At, B1); PG8_BAR;
;             PG8_LDB(B0, 1, 0); PG8_SCHED; PG8_LDA(At, 1, 0); PG8_STAGE(PG8_SA(0, 1), a2 + hstep, voffA);
;             PG8_WAIT_L(8); PG8_BAR; PG8_WAIT_L(0); PG8_MMA(0, 0, At, B0); PG8_BAR; PG8_SCHED;
;             PG8_LDB(B1, 1, 1); PG8_STAGE(PG8_SB(1, 0), b3, voffB);
;             PG8_BAR; PG8_WAIT_L(0); PG8_MMA(0, 1, At, B1); PG8_BAR;
	s_add_u32 s70, s60, 0x40000
	s_addc_u32 s71, s61, 0
	s_add_i32 s8, s8, s66
	v_lshl_add_u64 v[148:149], s[70:71], 0, v[0:1]
	s_mov_b32 m0, s8
	s_nop 0
	global_load_lds_dwordx4 v[148:149], off
	v_lshl_add_u64 v[148:149], s[70:71], 0, v[2:3]
	s_add_i32 m0, s8, 0x2000
	s_nop 0
	global_load_lds_dwordx4 v[148:149], off
	s_waitcnt vmcnt(6)
	s_barrier
	v_mfma_f32_16x16x32_bf16 v[64:67], v[198:201], v[164:167], v[64:67]
	v_mfma_f32_16x16x32_bf16 v[56:59], v[236:239], v[164:167], v[56:59]
	v_mfma_f32_16x16x32_bf16 v[48:51], v[198:201], v[172:175], v[48:51]
	v_mfma_f32_16x16x32_bf16 v[40:43], v[236:239], v[172:175], v[40:43]
	v_mfma_f32_16x16x32_bf16 v[32:35], v[198:201], v[180:183], v[32:35]
	v_mfma_f32_16x16x32_bf16 v[24:27], v[236:239], v[180:183], v[24:27]
	v_mfma_f32_16x16x32_bf16 v[16:19], v[198:201], v[190:193], v[16:19]
	v_mfma_f32_16x16x32_bf16 v[8:11], v[236:239], v[190:193], v[8:11]
	v_mfma_f32_16x16x32_bf16 v[64:67], v[232:235], v[168:171], v[64:67]
	v_mfma_f32_16x16x32_bf16 v[56:59], v[240:243], v[168:171], v[56:59]
	v_mfma_f32_16x16x32_bf16 v[48:51], v[232:235], v[176:179], v[48:51]
	v_mfma_f32_16x16x32_bf16 v[40:43], v[240:243], v[176:179], v[40:43]
	v_mfma_f32_16x16x32_bf16 v[32:35], v[232:235], v[186:189], v[32:35]
	v_mfma_f32_16x16x32_bf16 v[24:27], v[240:243], v[186:189], v[24:27]
	v_mfma_f32_16x16x32_bf16 v[16:19], v[232:235], v[194:197], v[16:19]
	v_mfma_f32_16x16x32_bf16 v[8:11], v[240:243], v[194:197], v[8:11]
	s_add_i32 s8, 0, 0x18000
	v_add_u32_e32 v160, s8, v145
	s_barrier
	ds_read_b128 v[148:151], v160
	ds_read_b128 v[152:155], v160 offset:1024
	ds_read_b128 v[156:159], v160 offset:2048
	ds_read_b128 v[160:163], v160 offset:3072
	s_add_u32 s62, s62, 0x40000
	s_addc_u32 s63, s63, 0
	s_mov_b32 m0, s68
	v_lshl_add_u64 v[198:199], s[62:63], 0, v[138:139]
	ds_read_b128 v[164:167], v147 offset:32768
	ds_read_b128 v[168:171], v147 offset:33792
	ds_read_b128 v[172:175], v147 offset:34816
	ds_read_b128 v[176:179], v147 offset:35840
	ds_read_b128 v[180:183], v147 offset:36864
	ds_read_b128 v[186:189], v147 offset:37888
	ds_read_b128 v[190:193], v147 offset:38912
	ds_read_b128 v[194:197], v147 offset:39936
	global_load_lds_dwordx4 v[198:199], off
	v_lshl_add_u64 v[198:199], s[62:63], 0, v[136:137]
	s_mov_b32 m0, s69
	s_nop 0
	global_load_lds_dwordx4 v[198:199], off
	s_waitcnt lgkmcnt(8)
	s_barrier
	s_waitcnt lgkmcnt(0)
	v_mfma_f32_16x16x32_bf16 v[132:135], v[148:151], v[164:167], v[132:135]
	v_mfma_f32_16x16x32_bf16 v[124:127], v[156:159], v[164:167], v[124:127]
	v_mfma_f32_16x16x32_bf16 v[116:119], v[148:151], v[172:175], v[116:119]
	v_mfma_f32_16x16x32_bf16 v[108:111], v[156:159], v[172:175], v[108:111]
	v_mfma_f32_16x16x32_bf16 v[100:103], v[148:151], v[180:183], v[100:103]
	v_mfma_f32_16x16x32_bf16 v[92:95], v[156:159], v[180:183], v[92:95]
	v_mfma_f32_16x16x32_bf16 v[84:87], v[148:151], v[190:193], v[84:87]
	v_mfma_f32_16x16x32_bf16 v[76:79], v[156:159], v[190:193], v[76:79]
	v_mfma_f32_16x16x32_bf16 v[132:135], v[152:155], v[168:171], v[132:135]
	v_mfma_f32_16x16x32_bf16 v[124:127], v[160:163], v[168:171], v[124:127]
	v_mfma_f32_16x16x32_bf16 v[116:119], v[152:155], v[176:179], v[116:119]
	v_mfma_f32_16x16x32_bf16 v[108:111], v[160:163], v[176:179], v[108:111]
	v_mfma_f32_16x16x32_bf16 v[100:103], v[152:155], v[186:189], v[100:103]
	v_mfma_f32_16x16x32_bf16 v[92:95], v[160:163], v[186:189], v[92:95]
	v_mfma_f32_16x16x32_bf16 v[84:87], v[152:155], v[194:197], v[84:87]
	v_mfma_f32_16x16x32_bf16 v[76:79], v[160:163], v[194:197], v[76:79]
	s_barrier
	s_add_i32 s29, 0, 0x1c000
	s_add_i32 s8, s8, s66
	v_add_u32_e32 v185, s29, v145
	v_lshl_add_u64 v[218:219], v[218:219], 0, s[12:13]
	s_mov_b32 m0, s8
	ds_read_b128 v[198:201], v185
	ds_read_b128 v[232:235], v185 offset:1024
	ds_read_b128 v[236:239], v185 offset:2048
	ds_read_b128 v[240:243], v185 offset:3072
	global_load_lds_dwordx4 v[218:219], off
	v_lshl_add_u64 v[218:219], v[244:245], 0, s[12:13]
	s_add_i32 m0, s8, 0x2000
	s_nop 0
	global_load_lds_dwordx4 v[218:219], off
	s_barrier
; #define PG8_STAGE(bufoff, gbase, voff) do { _Pragma("unroll") for (int _i = 0; _i < 2; ++_i) \
;         __builtin_amdgcn_global_load_lds((const unsigned*)((const char*)(gbase) + (voff)[_i]), (LAS unsigned*)(lds + (bufoff) + ldsw + _i * 8192), 16, 0, 0); } while (0)
; #define PG8_LDA(dst, b, h) do { _Pragma("unroll") for (int m = 0; m < 4; ++m) _Pragma("unroll") for (int k = 0; k < 2; ++k) dst[m][k] = *(const LAS bf16x8*)(lds + PG8_SA(b, h) + aoff + m * 2048 + k * 1024); } while (0)
; #define PG8_MMA(ai, bj, At, Bt) do { __builtin_amdgcn_s_setprio(1); _Pragma("unroll") for (int m = 0; m < 4; ++m) _Pragma("unroll") for (int n = 0; n < 2; ++n) _Pragma("unroll") for (int k = 0; k < 2; ++k) \
;         acc[ai][bj][m][n] = __builtin_amdgcn_mfma_f32_16x16x32_bf16(Bt[n][k], At[m][k], acc[ai][bj][m][n], 0, 0, 0); __builtin_amdgcn_s_setprio(0); } while (0)
; #define PG8_WAIT_V(n) asm volatile("s_waitcnt vmcnt(" #n ")" ::: "memory")
; #define PG8_WAIT_L(n) asm volatile("s_waitcnt lgkmcnt(" #n ")" ::: "memory")
; #define PG8_BAR __builtin_amdgcn_s_barrier()
; #define PG8_SCHED __builtin_amdgcn_sched_barrier(0)
; template <class Epi>
; __device__ __forceinline__ void gemm_phase(LAS unsigned char* lds, const Gemm g, const StaticOrder& S, const Epi& E) {
;     ...
;             PG8_BAR; PG8_WAIT_L(0); PG8_MMA(0, 1, At, B1); PG8_BAR;
;             PG8_LDA(At, 1, 1); PG8_STAGE(PG8_SA(1, 0), a3, voffA);
;             PG8_BAR; PG8_WAIT_L(0); PG8_MMA(1, 0, At, B0); PG8_BAR; PG8_SCHED;
;             PG8_STAGE(PG8_SB(1, 1), b3 + hstep, voffB);
;             PG8_WAIT_V(6); PG8_BAR; PG8_MMA(1, 1, At, B1); PG8_BAR;
	s_waitcnt lgkmcnt(0)
	v_mfma_f32_16x16x32_bf16 v[128:131], v[198:201], v[164:167], v[128:131]
	v_mfma_f32_16x16x32_bf16 v[120:123], v[236:239], v[164:167], v[120:123]
	v_mfma_f32_16x16x32_bf16 v[112:115], v[198:201], v[172:175], v[112:115]
	v_mfma_f32_16x16x32_bf16 v[104:107], v[236:239], v[172:175], v[104:107]
	v_mfma_f32_16x16x32_bf16 v[96:99], v[198:201], v[180:183], v[96:99]
	v_mfma_f32_16x16x32_bf16 v[88:91], v[236:239], v[180:183], v[88:91]
	v_mfma_f32_16x16x32_bf16 v[80:83], v[198:201], v[190:193], v[80:83]
	v_mfma_f32_16x16x32_bf16 v[72:75], v[236:239], v[190:193], v[72:75]
	v_mfma_f32_16x16x32_bf16 v[128:131], v[232:235], v[168:171], v[128:131]
	v_mfma_f32_16x16x32_bf16 v[120:123], v[240:243], v[168:171], v[120:123]
	v_mfma_f32_16x16x32_bf16 v[112:115], v[232:235], v[176:179], v[112:115]
	v_mfma_f32_16x16x32_bf16 v[104:107], v[240:243], v[176:179], v[104:107]
	v_mfma_f32_16x16x32_bf16 v[96:99], v[232:235], v[186:189], v[96:99]
	v_mfma_f32_16x16x32_bf16 v[88:91], v[240:243], v[186:189], v[88:91]
	v_mfma_f32_16x16x32_bf16 v[80:83], v[232:235], v[194:197], v[80:83]
	v_mfma_f32_16x16x32_bf16 v[72:75], v[240:243], v[194:197], v[72:75]
	s_mov_b32 m0, s6
	v_lshl_add_u64 v[218:219], v[246:247], 0, s[12:13]
	s_barrier
	ds_read_b128 v[164:167], v147 offset:49152
	ds_read_b128 v[168:171], v147 offset:50176
	ds_read_b128 v[172:175], v147 offset:51200
	ds_read_b128 v[176:179], v147 offset:52224
	ds_read_b128 v[180:183], v147 offset:53248
	ds_read_b128 v[186:189], v147 offset:54272
	ds_read_b128 v[190:193], v147 offset:55296
	ds_read_b128 v[194:197], v147 offset:56320
	global_load_lds_dwordx4 v[218:219], off
	v_lshl_add_u64 v[218:219], v[248:249], 0, s[12:13]
	s_mov_b32 m0, s18
	s_nop 0
	global_load_lds_dwordx4 v[218:219], off
	s_barrier
	s_waitcnt lgkmcnt(0)
	v_mfma_f32_16x16x32_bf16 v[68:71], v[148:151], v[164:167], v[68:71]
	v_mfma_f32_16x16x32_bf16 v[60:63], v[156:159], v[164:167], v[60:63]
	v_mfma_f32_16x16x32_bf16 v[52:55], v[148:151], v[172:175], v[52:55]
	v_mfma_f32_16x16x32_bf16 v[44:47], v[156:159], v[172:175], v[44:47]
	v_mfma_f32_16x16x32_bf16 v[36:39], v[148:151], v[180:183], v[36:39]
	v_mfma_f32_16x16x32_bf16 v[28:31], v[156:159], v[180:183], v[28:31]
	v_mfma_f32_16x16x32_bf16 v[20:23], v[148:151], v[190:193], v[20:23]
	v_mfma_f32_16x16x32_bf16 v[12:15], v[156:159], v[190:193], v[12:15]
	v_mfma_f32_16x16x32_bf16 v[68:71], v[152:155], v[168:171], v[68:71]
	v_mfma_f32_16x16x32_bf16 v[60:63], v[160:163], v[168:171], v[60:63]
	v_mfma_f32_16x16x32_bf16 v[52:55], v[152:155], v[176:179], v[52:55]
	v_mfma_f32_16x16x32_bf16 v[44:47], v[160:163], v[176:179], v[44:47]
	v_mfma_f32_16x16x32_bf16 v[36:39], v[152:155], v[186:189], v[36:39]
	v_mfma_f32_16x16x32_bf16 v[28:31], v[160:163], v[186:189], v[28:31]
	v_mfma_f32_16x16x32_bf16 v[20:23], v[152:155], v[194:197], v[20:23]
	v_mfma_f32_16x16x32_bf16 v[12:15], v[160:163], v[194:197], v[12:15]
	s_barrier
	s_add_u32 s60, s60, 0x40080
	s_addc_u32 s61, s61, 0
	s_add_i32 s8, s29, s66
	v_lshl_add_u64 v[148:149], s[60:61], 0, v[0:1]
	s_mov_b32 m0, s8
	s_nop 0
	global_load_lds_dwordx4 v[148:149], off
	v_lshl_add_u64 v[148:149], s[60:61], 0, v[2:3]
	s_add_i32 m0, s8, 0x2000
	s_nop 0
	global_load_lds_dwordx4 v[148:149], off
	s_waitcnt vmcnt(6)
	s_barrier
	v_mfma_f32_16x16x32_bf16 v[64:67], v[198:201], v[164:167], v[64:67]
	v_mfma_f32_16x16x32_bf16 v[56:59], v[236:239], v[164:167], v[56:59]
	v_mfma_f32_16x16x32_bf16 v[48:51], v[198:201], v[172:175], v[48:51]
	v_mfma_f32_16x16x32_bf16 v[40:43], v[236:239], v[172:175], v[40:43]
	v_mfma_f32_16x16x32_bf16 v[32:35], v[198:201], v[180:183], v[32:35]
	v_mfma_f32_16x16x32_bf16 v[24:27], v[236:239], v[180:183], v[24:27]
	v_mfma_f32_16x16x32_bf16 v[16:19], v[198:201], v[190:193], v[16:19]
	v_mfma_f32_16x16x32_bf16 v[8:11], v[236:239], v[190:193], v[8:11]
	v_mfma_f32_16x16x32_bf16 v[64:67], v[232:235], v[168:171], v[64:67]
	v_mfma_f32_16x16x32_bf16 v[56:59], v[240:243], v[168:171], v[56:59]
	v_mfma_f32_16x16x32_bf16 v[48:51], v[232:235], v[176:179], v[48:51]
	v_mfma_f32_16x16x32_bf16 v[40:43], v[240:243], v[176:179], v[40:43]
	v_mfma_f32_16x16x32_bf16 v[32:35], v[232:235], v[186:189], v[32:35]
	v_mfma_f32_16x16x32_bf16 v[24:27], v[240:243], v[186:189], v[24:27]
	v_mfma_f32_16x16x32_bf16 v[16:19], v[232:235], v[194:197], v[16:19]
	v_mfma_f32_16x16x32_bf16 v[8:11], v[240:243], v[194:197], v[8:11]
	s_add_u32 s24, s24, 0x100
	s_addc_u32 s25, s25, 0
	s_add_u32 s58, s58, 0x100
	s_addc_u32 s59, s59, 0
	s_cmp_ge_u32 s33, s1
	s_mov_b32 s29, s33
	s_barrier
	s_cbranch_scc0 .LBB0_1766
	s_branch .LBB0_1761

; #define PG8_STAGE(bufoff, gbase, voff) do { _Pragma("unroll") for (int _i = 0; _i < 2; ++_i) \
;         __builtin_amdgcn_global_load_lds((const unsigned*)((const char*)(gbase) + (voff)[_i]), (LAS unsigned*)(lds + (bufoff) + ldsw + _i * 8192), 16, 0, 0); } while (0)
; #define PG8_LDA(dst, b, h) do { _Pragma("unroll") for (int m = 0; m < 4; ++m) _Pragma("unroll") for (int k = 0; k < 2; ++k) dst[m][k] = *(const LAS bf16x8*)(lds + PG8_SA(b, h) + aoff + m * 2048 + k * 1024); } while (0)
; #define PG8_LDB(dst, b, h) do { _Pragma("unroll") for (int n = 0; n < 2; ++n) _Pragma("unroll") for (int k = 0; k < 2; ++k) dst[n][k] = *(const LAS bf16x8*)(lds + PG8_SB(b, h) + boff + n * 2048 + k * 1024); } while (0)
; #define PG8_MMA(ai, bj, At, Bt) do { __builtin_amdgcn_s_setprio(1); _Pragma("unroll") for (int m = 0; m < 4; ++m) _Pragma("unroll") for (int n = 0; n < 2; ++n) _Pragma("unroll") for (int k = 0; k < 2; ++k) \
;         acc[ai][bj][m][n] = __builtin_amdgcn_mfma_f32_16x16x32_bf16(Bt[n][k], At[m][k], acc[ai][bj][m][n], 0, 0, 0); __builtin_amdgcn_s_setprio(0); } while (0)
; #define PG8_WAIT_L(n) asm volatile("s_waitcnt lgkmcnt(" #n ")" ::: "memory")
; #define PG8_BAR __builtin_amdgcn_s_barrier()
; #define PG8_SCHED __builtin_amdgcn_sched_barrier(0)
; template <class Epi>
; __device__ __forceinline__ void gemm_phase(LAS unsigned char* lds, const Gemm g, const StaticOrder& S, const Epi& E) {
;     ...
;             const bool last = (t == nt - 2);
;             const char* a1 = cA + (size_t)(t + 1) * kstep;
;             const char* a2 = last ? nA : cA + (size_t)(t + 2) * kstep; const char* b2 = last ? nB : cB + (size_t)(t + 2) * kstep;
;             const char* a3 = a2 + kstep; const char* b3 = b2 + kstep;
;             PG8_LDB(B0, 0, 0); PG8_SCHED; PG8_LDA(At, 0, 0); PG8_STAGE(PG8_SA(1, 1), a1 + hstep, voffA);
;             PG8_WAIT_L(8); PG8_BAR; PG8_WAIT_L(0); PG8_MMA(0, 0, At, B0); PG8_BAR; PG8_SCHED;
;             PG8_LDB(B1, 0, 1); PG8_STAGE(PG8_SB(0, 0), b2, voffB);
;             PG8_BAR; PG8_WAIT_L(0); PG8_MMA(0, 1, At, B1); PG8_BAR;
;             PG8_LDA(At, 0, 1); PG8_STAGE(PG8_SA(0, 0), a2, voffA);
;             PG8_BAR; PG8_WAIT_L(0); PG8_MMA(1, 0, At, B0); PG8_BAR; PG8_SCHED;
.LBB0_1859:
	s_add_i32 s87, s60, 2
	s_add_u32 s58, s56, 0x100
	s_addc_u32 s59, s57, 0
	s_add_i32 s8, 0, 0x10000
	v_add_u32_e32 v148, s8, v231
	ds_read_b128 v[136:139], v148
	ds_read_b128 v[140:143], v148 offset:1024
	ds_read_b128 v[144:147], v148 offset:2048
	ds_read_b128 v[148:151], v148 offset:3072
	s_cmp_eq_u32 s74, s60
	s_cselect_b32 s60, s54, s75
	s_cselect_b32 s63, s49, s59
	s_cselect_b32 s62, s48, s58
	s_cselect_b32 s61, s55, s78
	v_lshl_add_u64 v[190:191], s[56:57], 0, v[188:189]
	s_add_i32 m0, s33, 0xc000
	ds_read_b128 v[152:155], v233
	ds_read_b128 v[156:159], v233 offset:1024
	ds_read_b128 v[160:163], v233 offset:2048
	ds_read_b128 v[164:167], v233 offset:3072
	ds_read_b128 v[168:171], v233 offset:4096
	ds_read_b128 v[172:175], v233 offset:5120
	ds_read_b128 v[176:179], v233 offset:6144
	ds_read_b128 v[180:183], v233 offset:7168
	global_load_lds_dwordx4 v[190:191], off
	v_lshl_add_u64 v[190:191], s[56:57], 0, v[186:187]
	s_add_i32 m0, s33, 0xe000
	s_nop 0
	global_load_lds_dwordx4 v[190:191], off
	s_waitcnt lgkmcnt(8)
	s_barrier
	s_waitcnt lgkmcnt(0)
	v_mfma_f32_16x16x32_bf16 v[132:135], v[136:139], v[152:155], v[132:135]
	v_mfma_f32_16x16x32_bf16 v[128:131], v[144:147], v[152:155], v[128:131]
	v_mfma_f32_16x16x32_bf16 v[116:119], v[136:139], v[160:163], v[116:119]
	v_mfma_f32_16x16x32_bf16 v[112:115], v[144:147], v[160:163], v[112:115]
	v_mfma_f32_16x16x32_bf16 v[100:103], v[136:139], v[168:171], v[100:103]
	v_mfma_f32_16x16x32_bf16 v[96:99], v[144:147], v[168:171], v[96:99]
	v_mfma_f32_16x16x32_bf16 v[84:87], v[136:139], v[176:179], v[84:87]
	v_mfma_f32_16x16x32_bf16 v[80:83], v[144:147], v[176:179], v[80:83]
	v_mfma_f32_16x16x32_bf16 v[132:135], v[140:143], v[156:159], v[132:135]
	v_mfma_f32_16x16x32_bf16 v[128:131], v[148:151], v[156:159], v[128:131]
	v_mfma_f32_16x16x32_bf16 v[116:119], v[140:143], v[164:167], v[116:119]
	v_mfma_f32_16x16x32_bf16 v[112:115], v[148:151], v[164:167], v[112:115]
	v_mfma_f32_16x16x32_bf16 v[100:103], v[140:143], v[172:175], v[100:103]
	v_mfma_f32_16x16x32_bf16 v[96:99], v[148:151], v[172:175], v[96:99]
	v_mfma_f32_16x16x32_bf16 v[84:87], v[140:143], v[180:183], v[84:87]
	v_mfma_f32_16x16x32_bf16 v[80:83], v[148:151], v[180:183], v[80:83]
	s_barrier
	s_add_i32 s89, 0, 0x14000
	v_add_u32_e32 v218, s89, v231
	s_add_i32 s8, s8, s3
	ds_read_b128 v[190:193], v218
	ds_read_b128 v[194:197], v218 offset:1024
	ds_read_b128 v[198:201], v218 offset:2048
	ds_read_b128 v[234:237], v218 offset:3072
	v_lshl_add_u64 v[218:219], s[60:61], 0, v[0:1]
	s_mov_b32 m0, s8
	v_lshl_add_u64 v[238:239], s[60:61], 0, v[2:3]
	global_load_lds_dwordx4 v[218:219], off
	s_add_i32 m0, s8, 0x2000
	s_nop 0
	global_load_lds_dwordx4 v[238:239], off
	s_barrier
	s_waitcnt lgkmcnt(0)
	v_mfma_f32_16x16x32_bf16 v[124:127], v[190:193], v[152:155], v[124:127]
	v_mfma_f32_16x16x32_bf16 v[120:123], v[198:201], v[152:155], v[120:123]
	v_mfma_f32_16x16x32_bf16 v[108:111], v[190:193], v[160:163], v[108:111]
	v_mfma_f32_16x16x32_bf16 v[104:107], v[198:201], v[160:163], v[104:107]
	v_mfma_f32_16x16x32_bf16 v[92:95], v[190:193], v[168:171], v[92:95]
	v_mfma_f32_16x16x32_bf16 v[88:91], v[198:201], v[168:171], v[88:91]
	v_mfma_f32_16x16x32_bf16 v[76:79], v[190:193], v[176:179], v[76:79]
	v_mfma_f32_16x16x32_bf16 v[72:75], v[198:201], v[176:179], v[72:75]
	v_mfma_f32_16x16x32_bf16 v[124:127], v[194:197], v[156:159], v[124:127]
	v_mfma_f32_16x16x32_bf16 v[120:123], v[234:237], v[156:159], v[120:123]
	v_mfma_f32_16x16x32_bf16 v[108:111], v[194:197], v[164:167], v[108:111]
	v_mfma_f32_16x16x32_bf16 v[104:107], v[234:237], v[164:167], v[104:107]
	v_mfma_f32_16x16x32_bf16 v[92:95], v[194:197], v[172:175], v[92:95]
	v_mfma_f32_16x16x32_bf16 v[88:91], v[234:237], v[172:175], v[88:91]
	v_mfma_f32_16x16x32_bf16 v[76:79], v[194:197], v[180:183], v[76:79]
	v_mfma_f32_16x16x32_bf16 v[72:75], v[234:237], v[180:183], v[72:75]
	s_mov_b32 m0, s33
	v_lshl_add_u64 v[240:241], s[62:63], 0, v[0:1]
	s_barrier
	ds_read_b128 v[152:155], v233 offset:16384
	ds_read_b128 v[156:159], v233 offset:17408
	ds_read_b128 v[160:163], v233 offset:18432
	ds_read_b128 v[164:167], v233 offset:19456
	ds_read_b128 v[168:171], v233 offset:20480
	ds_read_b128 v[172:175], v233 offset:21504
	ds_read_b128 v[176:179], v233 offset:22528
	ds_read_b128 v[180:183], v233 offset:23552
	global_load_lds_dwordx4 v[240:241], off
	v_lshl_add_u64 v[242:243], s[62:63], 0, v[2:3]
	s_mov_b32 m0, s68
	s_nop 0
	global_load_lds_dwordx4 v[242:243], off
	s_barrier
	s_waitcnt lgkmcnt(0)
	v_mfma_f32_16x16x32_bf16 v[68:71], v[136:139], v[152:155], v[68:71]
	v_mfma_f32_16x16x32_bf16 v[64:67], v[144:147], v[152:155], v[64:67]
	v_mfma_f32_16x16x32_bf16 v[52:55], v[136:139], v[160:163], v[52:55]
	v_mfma_f32_16x16x32_bf16 v[48:51], v[144:147], v[160:163], v[48:51]
	v_mfma_f32_16x16x32_bf16 v[36:39], v[136:139], v[168:171], v[36:39]
	v_mfma_f32_16x16x32_bf16 v[32:35], v[144:147], v[168:171], v[32:35]
	v_mfma_f32_16x16x32_bf16 v[20:23], v[136:139], v[176:179], v[20:23]
	v_mfma_f32_16x16x32_bf16 v[16:19], v[144:147], v[176:179], v[16:19]
	v_mfma_f32_16x16x32_bf16 v[68:71], v[140:143], v[156:159], v[68:71]
	v_mfma_f32_16x16x32_bf16 v[64:67], v[148:151], v[156:159], v[64:67]
	v_mfma_f32_16x16x32_bf16 v[52:55], v[140:143], v[164:167], v[52:55]
	v_mfma_f32_16x16x32_bf16 v[48:51], v[148:151], v[164:167], v[48:51]
	v_mfma_f32_16x16x32_bf16 v[36:39], v[140:143], v[172:175], v[36:39]
	v_mfma_f32_16x16x32_bf16 v[32:35], v[148:151], v[172:175], v[32:35]
	v_mfma_f32_16x16x32_bf16 v[20:23], v[140:143], v[180:183], v[20:23]
	v_mfma_f32_16x16x32_bf16 v[16:19], v[148:151], v[180:183], v[16:19]
	s_barrier
; #define PG8_STAGE(bufoff, gbase, voff) do { _Pragma("unroll") for (int _i = 0; _i < 2; ++_i) \
;         __builtin_amdgcn_global_load_lds((const unsigned*)((const char*)(gbase) + (voff)[_i]), (LAS unsigned*)(lds + (bufoff) + ldsw + _i * 8192), 16, 0, 0); } while (0)
; #define PG8_LDA(dst, b, h) do { _Pragma("unroll") for (int m = 0; m < 4; ++m) _Pragma("unroll") for (int k = 0; k < 2; ++k) dst[m][k] = *(const LAS bf16x8*)(lds + PG8_SA(b, h) + aoff + m * 2048 + k * 1024); } while (0)
; #define PG8_LDB(dst, b, h) do { _Pragma("unroll") for (int n = 0; n < 2; ++n) _Pragma("unroll") for (int k = 0; k < 2; ++k) dst[n][k] = *(const LAS bf16x8*)(lds + PG8_SB(b, h) + boff + n * 2048 + k * 1024); } while (0)
; #define PG8_MMA(ai, bj, At, Bt) do { __builtin_amdgcn_s_setprio(1); _Pragma("unroll") for (int m = 0; m < 4; ++m) _Pragma("unroll") for (int n = 0; n < 2; ++n) _Pragma("unroll") for (int k = 0; k < 2; ++k) \
;         acc[ai][bj][m][n] = __builtin_amdgcn_mfma_f32_16x16x32_bf16(Bt[n][k], At[m][k], acc[ai][bj][m][n], 0, 0, 0); __builtin_amdgcn_s_setprio(0); } while (0)
; #define PG8_WAIT_V(n) asm volatile("s_waitcnt vmcnt(" #n ")" ::: "memory")
; #define PG8_WAIT_L(n) asm volatile("s_waitcnt lgkmcnt(" #n ")" ::: "memory")
; #define PG8_BAR __builtin_amdgcn_s_barrier()
; #define PG8_SCHED __builtin_amdgcn_sched_barrier(0)
; template <class Epi>
; __device__ __forceinline__ void gemm_phase(LAS unsigned char* lds, const Gemm g, const StaticOrder& S, const Epi& E) {
;     ...
;             PG8_STAGE(PG8_SB(0, 1), b2 + hstep, voffB);
;             PG8_WAIT_V(6); PG8_BAR; PG8_MMA(1, 1, At, B1); PG8_BAR;
;             PG8_LDB(B0, 1, 0); PG8_SCHED; PG8_LDA(At, 1, 0); PG8_STAGE(PG8_SA(0, 1), a2 + hstep, voffA);
;             PG8_WAIT_L(8); PG8_BAR; PG8_WAIT_L(0); PG8_MMA(0, 0, At, B0); PG8_BAR; PG8_SCHED;
;             PG8_LDB(B1, 1, 1); PG8_STAGE(PG8_SB(1, 0), b3, voffB);
;             PG8_BAR; PG8_WAIT_L(0); PG8_MMA(0, 1, At, B1); PG8_BAR;
	s_add_u32 s56, s60, 0xb0000
	s_addc_u32 s57, s61, 0
	s_add_i32 s8, s89, s3
	v_lshl_add_u64 v[136:137], s[56:57], 0, v[0:1]
	s_mov_b32 m0, s8
	s_nop 0
	global_load_lds_dwordx4 v[136:137], off
	v_lshl_add_u64 v[136:137], s[56:57], 0, v[2:3]
	s_add_i32 m0, s8, 0x2000
	s_nop 0
	global_load_lds_dwordx4 v[136:137], off
	s_waitcnt vmcnt(6)
	s_barrier
	v_mfma_f32_16x16x32_bf16 v[60:63], v[190:193], v[152:155], v[60:63]
	v_mfma_f32_16x16x32_bf16 v[56:59], v[198:201], v[152:155], v[56:59]
	v_mfma_f32_16x16x32_bf16 v[44:47], v[190:193], v[160:163], v[44:47]
	v_mfma_f32_16x16x32_bf16 v[40:43], v[198:201], v[160:163], v[40:43]
	v_mfma_f32_16x16x32_bf16 v[28:31], v[190:193], v[168:171], v[28:31]
	v_mfma_f32_16x16x32_bf16 v[24:27], v[198:201], v[168:171], v[24:27]
	v_mfma_f32_16x16x32_bf16 v[12:15], v[190:193], v[176:179], v[12:15]
	v_mfma_f32_16x16x32_bf16 v[8:11], v[198:201], v[176:179], v[8:11]
	v_mfma_f32_16x16x32_bf16 v[60:63], v[194:197], v[156:159], v[60:63]
	v_mfma_f32_16x16x32_bf16 v[56:59], v[234:237], v[156:159], v[56:59]
	v_mfma_f32_16x16x32_bf16 v[44:47], v[194:197], v[164:167], v[44:47]
	v_mfma_f32_16x16x32_bf16 v[40:43], v[234:237], v[164:167], v[40:43]
	v_mfma_f32_16x16x32_bf16 v[28:31], v[194:197], v[172:175], v[28:31]
	v_mfma_f32_16x16x32_bf16 v[24:27], v[234:237], v[172:175], v[24:27]
	v_mfma_f32_16x16x32_bf16 v[12:15], v[194:197], v[180:183], v[12:15]
	v_mfma_f32_16x16x32_bf16 v[8:11], v[234:237], v[180:183], v[8:11]
	s_add_i32 s8, 0, 0x18000
	v_add_u32_e32 v148, s8, v231
	s_barrier
	ds_read_b128 v[136:139], v148
	ds_read_b128 v[140:143], v148 offset:1024
	ds_read_b128 v[144:147], v148 offset:2048
	ds_read_b128 v[148:151], v148 offset:3072
	s_add_u32 s56, s62, 0xb0000
	s_addc_u32 s57, s63, 0
	s_mov_b32 m0, s18
	v_lshl_add_u64 v[190:191], s[56:57], 0, v[0:1]
	ds_read_b128 v[152:155], v233 offset:32768
	ds_read_b128 v[156:159], v233 offset:33792
	ds_read_b128 v[160:163], v233 offset:34816
	ds_read_b128 v[164:167], v233 offset:35840
	ds_read_b128 v[168:171], v233 offset:36864
	ds_read_b128 v[172:175], v233 offset:37888
	ds_read_b128 v[176:179], v233 offset:38912
	ds_read_b128 v[180:183], v233 offset:39936
	global_load_lds_dwordx4 v[190:191], off
	v_lshl_add_u64 v[190:191], s[56:57], 0, v[2:3]
	s_mov_b32 m0, s19
	s_nop 0
	global_load_lds_dwordx4 v[190:191], off
	s_waitcnt lgkmcnt(8)
	s_barrier
	s_waitcnt lgkmcnt(0)
	v_mfma_f32_16x16x32_bf16 v[132:135], v[136:139], v[152:155], v[132:135]
	v_mfma_f32_16x16x32_bf16 v[128:131], v[144:147], v[152:155], v[128:131]
	v_mfma_f32_16x16x32_bf16 v[116:119], v[136:139], v[160:163], v[116:119]
	v_mfma_f32_16x16x32_bf16 v[112:115], v[144:147], v[160:163], v[112:115]
	v_mfma_f32_16x16x32_bf16 v[100:103], v[136:139], v[168:171], v[100:103]
	v_mfma_f32_16x16x32_bf16 v[96:99], v[144:147], v[168:171], v[96:99]
	v_mfma_f32_16x16x32_bf16 v[84:87], v[136:139], v[176:179], v[84:87]
	v_mfma_f32_16x16x32_bf16 v[80:83], v[144:147], v[176:179], v[80:83]
	v_mfma_f32_16x16x32_bf16 v[132:135], v[140:143], v[156:159], v[132:135]
	v_mfma_f32_16x16x32_bf16 v[128:131], v[148:151], v[156:159], v[128:131]
	v_mfma_f32_16x16x32_bf16 v[116:119], v[140:143], v[164:167], v[116:119]
	v_mfma_f32_16x16x32_bf16 v[112:115], v[148:151], v[164:167], v[112:115]
	v_mfma_f32_16x16x32_bf16 v[100:103], v[140:143], v[172:175], v[100:103]
	v_mfma_f32_16x16x32_bf16 v[96:99], v[148:151], v[172:175], v[96:99]
	v_mfma_f32_16x16x32_bf16 v[84:87], v[140:143], v[180:183], v[84:87]
	v_mfma_f32_16x16x32_bf16 v[80:83], v[148:151], v[180:183], v[80:83]
	s_barrier
	s_add_i32 s62, 0, 0x1c000
	s_add_i32 s8, s8, s3
	v_add_u32_e32 v234, s62, v231
	v_lshl_add_u64 v[218:219], v[218:219], 0, s[12:13]
	s_mov_b32 m0, s8
	ds_read_b128 v[190:193], v234
	ds_read_b128 v[194:197], v234 offset:1024
	ds_read_b128 v[198:201], v234 offset:2048
	ds_read_b128 v[234:237], v234 offset:3072
	global_load_lds_dwordx4 v[218:219], off
	v_lshl_add_u64 v[218:219], v[238:239], 0, s[12:13]
	s_add_i32 m0, s8, 0x2000
	s_nop 0
	global_load_lds_dwordx4 v[218:219], off
	s_barrier
; #define PG8_STAGE(bufoff, gbase, voff) do { _Pragma("unroll") for (int _i = 0; _i < 2; ++_i) \
;         __builtin_amdgcn_global_load_lds((const unsigned*)((const char*)(gbase) + (voff)[_i]), (LAS unsigned*)(lds + (bufoff) + ldsw + _i * 8192), 16, 0, 0); } while (0)
; #define PG8_LDA(dst, b, h) do { _Pragma("unroll") for (int m = 0; m < 4; ++m) _Pragma("unroll") for (int k = 0; k < 2; ++k) dst[m][k] = *(const LAS bf16x8*)(lds + PG8_SA(b, h) + aoff + m * 2048 + k * 1024); } while (0)
; #define PG8_MMA(ai, bj, At, Bt) do { __builtin_amdgcn_s_setprio(1); _Pragma("unroll") for (int m = 0; m < 4; ++m) _Pragma("unroll") for (int n = 0; n < 2; ++n) _Pragma("unroll") for (int k = 0; k < 2; ++k) \
;         acc[ai][bj][m][n] = __builtin_amdgcn_mfma_f32_16x16x32_bf16(Bt[n][k], At[m][k], acc[ai][bj][m][n], 0, 0, 0); __builtin_amdgcn_s_setprio(0); } while (0)
; #define PG8_WAIT_V(n) asm volatile("s_waitcnt vmcnt(" #n ")" ::: "memory")
; #define PG8_WAIT_L(n) asm volatile("s_waitcnt lgkmcnt(" #n ")" ::: "memory")
; #define PG8_BAR __builtin_amdgcn_s_barrier()
; #define PG8_SCHED __builtin_amdgcn_sched_barrier(0)
; template <class Epi>
; __device__ __forceinline__ void gemm_phase(LAS unsigned char* lds, const Gemm g, const StaticOrder& S, const Epi& E) {
;     ...
;             PG8_BAR; PG8_WAIT_L(0); PG8_MMA(0, 1, At, B1); PG8_BAR;
;             PG8_LDA(At, 1, 1); PG8_STAGE(PG8_SA(1, 0), a3, voffA);
;             PG8_BAR; PG8_WAIT_L(0); PG8_MMA(1, 0, At, B0); PG8_BAR; PG8_SCHED;
;             PG8_STAGE(PG8_SB(1, 1), b3 + hstep, voffB);
;             PG8_WAIT_V(6); PG8_BAR; PG8_MMA(1, 1, At, B1); PG8_BAR;
	s_waitcnt lgkmcnt(0)
	v_mfma_f32_16x16x32_bf16 v[124:127], v[190:193], v[152:155], v[124:127]
	v_mfma_f32_16x16x32_bf16 v[120:123], v[198:201], v[152:155], v[120:123]
	v_mfma_f32_16x16x32_bf16 v[108:111], v[190:193], v[160:163], v[108:111]
	v_mfma_f32_16x16x32_bf16 v[104:107], v[198:201], v[160:163], v[104:107]
	v_mfma_f32_16x16x32_bf16 v[92:95], v[190:193], v[168:171], v[92:95]
	v_mfma_f32_16x16x32_bf16 v[88:91], v[198:201], v[168:171], v[88:91]
	v_mfma_f32_16x16x32_bf16 v[76:79], v[190:193], v[176:179], v[76:79]
	v_mfma_f32_16x16x32_bf16 v[72:75], v[198:201], v[176:179], v[72:75]
	v_mfma_f32_16x16x32_bf16 v[124:127], v[194:197], v[156:159], v[124:127]
	v_mfma_f32_16x16x32_bf16 v[120:123], v[234:237], v[156:159], v[120:123]
	v_mfma_f32_16x16x32_bf16 v[108:111], v[194:197], v[164:167], v[108:111]
	v_mfma_f32_16x16x32_bf16 v[104:107], v[234:237], v[164:167], v[104:107]
	v_mfma_f32_16x16x32_bf16 v[92:95], v[194:197], v[172:175], v[92:95]
	v_mfma_f32_16x16x32_bf16 v[88:91], v[234:237], v[172:175], v[88:91]
	v_mfma_f32_16x16x32_bf16 v[76:79], v[194:197], v[180:183], v[76:79]
	v_mfma_f32_16x16x32_bf16 v[72:75], v[234:237], v[180:183], v[72:75]
	s_mov_b32 m0, s23
	v_lshl_add_u64 v[218:219], v[240:241], 0, s[12:13]
	s_barrier
	ds_read_b128 v[152:155], v233 offset:49152
	ds_read_b128 v[156:159], v233 offset:50176
	ds_read_b128 v[160:163], v233 offset:51200
	ds_read_b128 v[164:167], v233 offset:52224
	ds_read_b128 v[168:171], v233 offset:53248
	ds_read_b128 v[172:175], v233 offset:54272
	ds_read_b128 v[176:179], v233 offset:55296
	ds_read_b128 v[180:183], v233 offset:56320
	global_load_lds_dwordx4 v[218:219], off
	v_lshl_add_u64 v[218:219], v[242:243], 0, s[12:13]
	s_mov_b32 m0, s70
	s_nop 0
	global_load_lds_dwordx4 v[218:219], off
	s_barrier
	s_waitcnt lgkmcnt(0)
	v_mfma_f32_16x16x32_bf16 v[68:71], v[136:139], v[152:155], v[68:71]
	v_mfma_f32_16x16x32_bf16 v[64:67], v[144:147], v[152:155], v[64:67]
	v_mfma_f32_16x16x32_bf16 v[52:55], v[136:139], v[160:163], v[52:55]
	v_mfma_f32_16x16x32_bf16 v[48:51], v[144:147], v[160:163], v[48:51]
	v_mfma_f32_16x16x32_bf16 v[36:39], v[136:139], v[168:171], v[36:39]
	v_mfma_f32_16x16x32_bf16 v[32:35], v[144:147], v[168:171], v[32:35]
	v_mfma_f32_16x16x32_bf16 v[20:23], v[136:139], v[176:179], v[20:23]
	v_mfma_f32_16x16x32_bf16 v[16:19], v[144:147], v[176:179], v[16:19]
	v_mfma_f32_16x16x32_bf16 v[68:71], v[140:143], v[156:159], v[68:71]
	v_mfma_f32_16x16x32_bf16 v[64:67], v[148:151], v[156:159], v[64:67]
	v_mfma_f32_16x16x32_bf16 v[52:55], v[140:143], v[164:167], v[52:55]
	v_mfma_f32_16x16x32_bf16 v[48:51], v[148:151], v[164:167], v[48:51]
	v_mfma_f32_16x16x32_bf16 v[36:39], v[140:143], v[172:175], v[36:39]
	v_mfma_f32_16x16x32_bf16 v[32:35], v[148:151], v[172:175], v[32:35]
	v_mfma_f32_16x16x32_bf16 v[20:23], v[140:143], v[180:183], v[20:23]
	v_mfma_f32_16x16x32_bf16 v[16:19], v[148:151], v[180:183], v[16:19]
	s_barrier
	s_add_u32 s56, s60, 0xb0080
	s_addc_u32 s57, s61, 0
	s_add_i32 s8, s62, s3
	v_lshl_add_u64 v[136:137], s[56:57], 0, v[0:1]
	s_mov_b32 m0, s8
	s_nop 0
	global_load_lds_dwordx4 v[136:137], off
	v_lshl_add_u64 v[136:137], s[56:57], 0, v[2:3]
	s_add_i32 m0, s8, 0x2000
	s_nop 0
	global_load_lds_dwordx4 v[136:137], off
	s_waitcnt vmcnt(6)
	s_barrier
	v_mfma_f32_16x16x32_bf16 v[60:63], v[190:193], v[152:155], v[60:63]
	v_mfma_f32_16x16x32_bf16 v[56:59], v[198:201], v[152:155], v[56:59]
	v_mfma_f32_16x16x32_bf16 v[44:47], v[190:193], v[160:163], v[44:47]
	v_mfma_f32_16x16x32_bf16 v[40:43], v[198:201], v[160:163], v[40:43]
	v_mfma_f32_16x16x32_bf16 v[28:31], v[190:193], v[168:171], v[28:31]
	v_mfma_f32_16x16x32_bf16 v[24:27], v[198:201], v[168:171], v[24:27]
	v_mfma_f32_16x16x32_bf16 v[12:15], v[190:193], v[176:179], v[12:15]
	v_mfma_f32_16x16x32_bf16 v[8:11], v[198:201], v[176:179], v[8:11]
	v_mfma_f32_16x16x32_bf16 v[60:63], v[194:197], v[156:159], v[60:63]
	v_mfma_f32_16x16x32_bf16 v[56:59], v[234:237], v[156:159], v[56:59]
	v_mfma_f32_16x16x32_bf16 v[44:47], v[194:197], v[164:167], v[44:47]
	v_mfma_f32_16x16x32_bf16 v[40:43], v[234:237], v[164:167], v[40:43]
	v_mfma_f32_16x16x32_bf16 v[28:31], v[194:197], v[172:175], v[28:31]
	v_mfma_f32_16x16x32_bf16 v[24:27], v[234:237], v[172:175], v[24:27]
	v_mfma_f32_16x16x32_bf16 v[12:15], v[194:197], v[180:183], v[12:15]
	v_mfma_f32_16x16x32_bf16 v[8:11], v[234:237], v[180:183], v[8:11]
	s_add_u32 s75, s75, 0x100
	s_addc_u32 s78, s78, 0
	s_cmp_ge_i32 s87, s73
	s_mov_b64 s[56:57], s[58:59]
	s_mov_b32 s60, s87
	s_barrier
	s_cbranch_scc0 .LBB0_1859
	v_readlane_b32 s78, v255, 24
	s_mov_b32 s87, 0x8000
